# adds: phase3 sample tile loads issued up front, no L2 write-back at barriers after write-through phases, K-loop per-block setprio toggles removed + static priority for waves 4-7, counted wait at GEMM1
# speedup vs baseline: 1.4635x; 1.0122x over previous
.LBB0_608:
	s_and_b64 vcc, exec, s[0:1]
	s_cbranch_vccnz .LBB0_665
	v_ashrrev_i32_e32 v3, 31, v10
	v_lshrrev_b32_e32 v3, 26, v3
	v_add_u32_e32 v3, v10, v3
	v_ashrrev_i32_e32 v11, 6, v3
	v_bfe_i32 v3, v10, 27, 1
	v_lshlrev_b32_e32 v2, 4, v10
	v_lshrrev_b32_e32 v3, 22, v3
	v_add_u32_e32 v3, v2, v3
	v_and_b32_e32 v3, 0xfffffc00, v3
	v_sub_u32_e32 v3, v2, v3
	v_lshrrev_b32_e32 v4, 4, v3
	v_bitop3_b32 v4, v4, v3, 32 bitop3:0x6c
	v_ashrrev_i32_e32 v3, 31, v3
	v_lshrrev_b32_e32 v3, 26, v3
	v_add_u32_e32 v3, v4, v3
	v_ashrrev_i32_e32 v12, 6, v3
	v_lshlrev_b32_e32 v5, 3, v11
	v_mul_i32_i24_e32 v6, 64, v12
	v_and_b32_e32 v5, -16, v5
	v_sub_u32_e32 v4, v4, v6
	v_readlane_b32 s1, v242, 40
	v_add_u32_e32 v3, v12, v5
	v_lshlrev_b32_e32 v5, 5, v11
	v_ashrrev_i16_sdwa v4, v180, sext(v4) dst_sel:DWORD dst_unused:UNUSED_PAD src0_sel:DWORD src1_sel:BYTE_0
	s_mul_i32 s0, s1, 0x700000
	v_and_b32_e32 v5, 32, v5
	v_bfe_i32 v13, v4, 0, 16
	s_add_u32 s6, s52, s0
	v_and_b32_e32 v7, 3, v12
	s_mov_b32 s0, 0x1fffe0
	v_add_lshl_u32 v5, v5, v13, 1
	v_add_u32_e32 v2, 0x2000, v2
	v_lshlrev_b32_e32 v4, 1, v3
	v_lshrrev_b32_e32 v6, 2, v3
	v_and_or_b32 v7, v3, s0, v7
	v_lshl_add_u32 v134, v3, 11, v5
	v_ashrrev_i32_e32 v3, 31, v2
	v_lshrrev_b32_e32 v3, 22, v3
	v_add_u32_e32 v3, v2, v3
	v_ashrrev_i32_e32 v14, 10, v3
	v_mul_i32_i24_e32 v3, 0x400, v14
	v_sub_u32_e32 v2, v2, v3
	v_and_b32_e32 v4, 24, v4
	v_and_b32_e32 v6, 4, v6
	v_lshrrev_b32_e32 v3, 4, v2
	v_or3_b32 v4, v7, v6, v4
	v_bitop3_b32 v2, v3, v2, 32 bitop3:0x6c
	v_lshl_add_u32 v154, v4, 11, v5
	v_ashrrev_i32_e32 v4, 31, v2
	v_lshrrev_b32_e32 v4, 26, v4
	v_lshlrev_b32_e32 v3, 3, v14
	v_add_u32_e32 v4, v2, v4
	v_and_b32_e32 v3, -16, v3
	v_ashrrev_i32_e32 v15, 6, v4
	s_addc_u32 s7, s53, 0
	s_ashr_i32 s2, s3, 8
	v_add_u32_e32 v3, v15, v3
	v_and_b32_e32 v6, 3, v15
	s_ashr_i32 s12, s3, 6
	v_and_or_b32 v6, v3, s0, v6
	v_writelane_b32 v242, s3, 51
	s_lshl_b32 s5, s12, 10
	s_lshl_b32 s3, s2, 6
	s_mul_i32 s0, s1, 0x10800
	v_readlane_b32 s16, v244, 0
	v_and_b32_e32 v4, 0xc0, v4
	v_readlane_b32 s17, v244, 1
	s_add_u32 s0, s16, s0
	v_sub_u32_e32 v2, v2, v4
	v_readlane_b32 s18, v244, 2
	v_readlane_b32 s19, v244, 3
	s_addc_u32 s1, s17, 0
	s_ashr_i32 s35, s34, 31
	s_ashr_i32 s11, s10, 31
	v_ashrrev_i16_sdwa v2, v180, sext(v2) dst_sel:DWORD dst_unused:UNUSED_PAD src0_sel:DWORD src1_sel:BYTE_0
	s_lshl_b64 s[18:19], s[34:35], 19
	s_lshl_b64 s[16:17], s[10:11], 19
	v_lshlrev_b32_e32 v5, 5, v14
	v_bfe_i32 v16, v2, 0, 16
	v_lshlrev_b32_e32 v2, 1, v3
	v_lshrrev_b32_e32 v4, 2, v3
	s_add_u32 s16, s6, s16
	v_and_b32_e32 v5, 32, v5
	v_and_b32_e32 v2, 24, v2
	v_and_b32_e32 v4, 4, v4
	s_addc_u32 s17, s7, s17
	s_lshl_b32 s4, s34, 8
	v_or3_b32 v2, v6, v4, v2
	v_add_lshl_u32 v4, v5, v16, 1
	v_and_b32_e32 v17, 15, v10
	s_add_i32 s4, s4, s3
	v_lshl_add_u32 v138, v2, 11, v4
	v_or_b32_e32 v2, s4, v17
	v_lshl_add_u32 v136, v3, 11, v4
	v_ashrrev_i32_e32 v3, 31, v2
	s_add_i32 s35, s5, 32
	v_lshl_add_u64 v[2:3], v[2:3], 2, s[0:1]
	s_add_i32 m0, s35, 0x10000
	global_load_dword v130, v[2:3], off
	global_load_dword v168, v[2:3], off offset:64
	global_load_dword v167, v[2:3], off offset:128
	global_load_dword v166, v[2:3], off offset:192
	global_load_dword v165, v[2:3], off offset:512
	global_load_dword v164, v[2:3], off offset:576
	global_load_dword v153, v[2:3], off offset:640
	global_load_dword v152, v[2:3], off offset:704
	v_mov_b32_e32 v139, v155
	global_load_lds_dwordx4 v154, s[16:17]
	s_add_i32 m0, s35, 0x12000
	s_add_u32 s30, s58, s18
	global_load_lds_dwordx4 v138, s[16:17]
	s_addc_u32 s31, s59, s19
	s_mov_b32 m0, s35
	s_add_i32 s14, s35, 0x2000
	global_load_lds_dwordx4 v134, s[30:31]
	s_mov_b32 m0, s14
	s_add_u32 s18, s16, 0x40000
	global_load_lds_dwordx4 v136, s[30:31]
	s_addc_u32 s19, s17, 0
	s_add_i32 m0, s35, 0x14000
	v_mov_b32_e32 v135, v155
	global_load_lds_dwordx4 v154, s[18:19]
	s_add_i32 m0, s35, 0x16000
	v_mov_b32_e32 v137, v155
	global_load_lds_dwordx4 v138, s[18:19]
	s_add_u32 s18, s30, 0x40000
	s_addc_u32 s19, s31, 0
	s_add_i32 s4, s35, 0x4000
	s_mov_b32 m0, s4
	s_add_i32 s20, s35, 0x6000
	global_load_lds_dwordx4 v134, s[18:19]
	s_mov_b32 m0, s20
	v_lshl_add_u64 v[8:9], s[16:17], 0, v[154:155]
	global_load_lds_dwordx4 v136, s[18:19]
	v_lshl_add_u64 v[6:7], s[16:17], 0, v[138:139]
	v_lshl_add_u64 v[4:5], s[30:31], 0, v[134:135]
	s_cmp_lg_u32 s2, 1
	v_lshl_add_u64 v[2:3], s[30:31], 0, v[136:137]
	s_cbranch_scc1 .LBB0_611
	s_barrier
	s_setprio 1

.LBB0_620:
	s_add_u32 s2, s30, 0xfffc0080
	s_addc_u32 s3, s31, -1
	s_add_i32 s94, 32, 0x10000
	v_add_u32_e32 v131, s94, v145
	ds_read_b128 v[170:173], v131
	ds_read_b128 v[174:177], v131 offset:1024
	ds_read_b128 v[182:185], v131 offset:2048
	ds_read_b128 v[186:189], v131 offset:3072
	s_cmp_eq_u32 s39, 12
	s_cselect_b32 s3, s11, s3
	s_cselect_b32 s2, s18, s2
	s_cselect_b32 s17, s13, s29
	s_cselect_b32 s16, s19, s28
	v_lshl_add_u64 v[132:133], s[30:31], 0, v[140:141]
	s_add_i32 m0, s35, 0xc000
	ds_read_b128 v[190:193], v151
	ds_read_b128 v[194:197], v151 offset:1024
	ds_read_b128 v[198:201], v151 offset:2048
	ds_read_b128 v[202:205], v151 offset:3072
	ds_read_b128 v[206:209], v151 offset:4096
	ds_read_b128 v[210:213], v151 offset:5120
	ds_read_b128 v[214:217], v151 offset:6144
	ds_read_b128 v[218:221], v151 offset:7168
	global_load_lds_dwordx4 v[132:133], off
	v_lshl_add_u64 v[132:133], s[30:31], 0, v[142:143]
	s_add_i32 m0, s35, 0xe000
	s_nop 0
	global_load_lds_dwordx4 v[132:133], off
	s_waitcnt lgkmcnt(8)
	s_barrier
	s_waitcnt lgkmcnt(0)
	s_waitcnt lgkmcnt(0)
	v_mfma_f32_16x16x32_bf16 v[126:129], v[170:173], v[190:193], v[126:129]
	v_mfma_f32_16x16x32_bf16 v[122:125], v[182:185], v[190:193], v[122:125]
	v_mfma_f32_16x16x32_bf16 v[110:113], v[170:173], v[198:201], v[110:113]
	v_mfma_f32_16x16x32_bf16 v[106:109], v[182:185], v[198:201], v[106:109]
	v_mfma_f32_16x16x32_bf16 v[94:97], v[170:173], v[206:209], v[94:97]
	v_mfma_f32_16x16x32_bf16 v[90:93], v[182:185], v[206:209], v[90:93]
	v_mfma_f32_16x16x32_bf16 v[78:81], v[170:173], v[214:217], v[78:81]
	v_mfma_f32_16x16x32_bf16 v[74:77], v[182:185], v[214:217], v[74:77]
	v_mfma_f32_16x16x32_bf16 v[126:129], v[174:177], v[194:197], v[126:129]
	v_mfma_f32_16x16x32_bf16 v[122:125], v[186:189], v[194:197], v[122:125]
	v_mfma_f32_16x16x32_bf16 v[110:113], v[174:177], v[202:205], v[110:113]
	v_mfma_f32_16x16x32_bf16 v[106:109], v[186:189], v[202:205], v[106:109]
	v_mfma_f32_16x16x32_bf16 v[94:97], v[174:177], v[210:213], v[94:97]
	v_mfma_f32_16x16x32_bf16 v[90:93], v[186:189], v[210:213], v[90:93]
	v_mfma_f32_16x16x32_bf16 v[78:81], v[174:177], v[218:221], v[78:81]
	v_mfma_f32_16x16x32_bf16 v[74:77], v[186:189], v[218:221], v[74:77]
	s_barrier
	s_add_i32 vcc_lo, 32, 0x14000
	s_add_i32 s94, s94, s5
	v_add_u32_e32 v131, vcc_lo, v145
	v_lshl_add_u64 v[132:133], s[16:17], 0, v[154:155]
	s_mov_b32 m0, s94
	ds_read_b128 v[222:225], v131
	ds_read_b128 v[226:229], v131 offset:1024
	ds_read_b128 v[230:233], v131 offset:2048
	ds_read_b128 v[234:237], v131 offset:3072
	global_load_lds_dwordx4 v[132:133], off
	v_lshl_add_u64 v[178:179], s[16:17], 0, v[138:139]
	s_add_i32 m0, s94, 0x2000
	s_nop 0
	global_load_lds_dwordx4 v[178:179], off
	s_barrier
	s_waitcnt lgkmcnt(0)
	s_waitcnt lgkmcnt(0)
	v_mfma_f32_16x16x32_bf16 v[118:121], v[222:225], v[190:193], v[118:121]
	v_mfma_f32_16x16x32_bf16 v[114:117], v[230:233], v[190:193], v[114:117]
	v_mfma_f32_16x16x32_bf16 v[102:105], v[222:225], v[198:201], v[102:105]
	v_mfma_f32_16x16x32_bf16 v[98:101], v[230:233], v[198:201], v[98:101]
	v_mfma_f32_16x16x32_bf16 v[86:89], v[222:225], v[206:209], v[86:89]
	v_mfma_f32_16x16x32_bf16 v[82:85], v[230:233], v[206:209], v[82:85]
	v_mfma_f32_16x16x32_bf16 v[70:73], v[222:225], v[214:217], v[70:73]
	v_mfma_f32_16x16x32_bf16 v[66:69], v[230:233], v[214:217], v[66:69]
	v_mfma_f32_16x16x32_bf16 v[118:121], v[226:229], v[194:197], v[118:121]
	v_mfma_f32_16x16x32_bf16 v[114:117], v[234:237], v[194:197], v[114:117]
	v_mfma_f32_16x16x32_bf16 v[102:105], v[226:229], v[202:205], v[102:105]
	v_mfma_f32_16x16x32_bf16 v[98:101], v[234:237], v[202:205], v[98:101]
	v_mfma_f32_16x16x32_bf16 v[86:89], v[226:229], v[210:213], v[86:89]
	v_mfma_f32_16x16x32_bf16 v[82:85], v[234:237], v[210:213], v[82:85]
	v_mfma_f32_16x16x32_bf16 v[70:73], v[226:229], v[218:221], v[70:73]
	v_mfma_f32_16x16x32_bf16 v[66:69], v[234:237], v[218:221], v[66:69]
	s_mov_b32 m0, s35
	v_lshl_add_u64 v[238:239], s[2:3], 0, v[134:135]
	s_barrier
	ds_read_b128 v[190:193], v151 offset:16384
	ds_read_b128 v[194:197], v151 offset:17408
	ds_read_b128 v[198:201], v151 offset:18432
	ds_read_b128 v[202:205], v151 offset:19456
	ds_read_b128 v[206:209], v151 offset:20480
	ds_read_b128 v[210:213], v151 offset:21504
	ds_read_b128 v[214:217], v151 offset:22528
	ds_read_b128 v[218:221], v151 offset:23552
	global_load_lds_dwordx4 v[238:239], off
	v_lshl_add_u64 v[240:241], s[2:3], 0, v[136:137]
	s_mov_b32 m0, s14
	s_nop 0
	global_load_lds_dwordx4 v[240:241], off
	s_barrier
	s_waitcnt lgkmcnt(0)
	s_waitcnt lgkmcnt(0)
	v_mfma_f32_16x16x32_bf16 v[62:65], v[170:173], v[190:193], v[62:65]
	v_mfma_f32_16x16x32_bf16 v[58:61], v[182:185], v[190:193], v[58:61]
	v_mfma_f32_16x16x32_bf16 v[46:49], v[170:173], v[198:201], v[46:49]
	v_mfma_f32_16x16x32_bf16 v[42:45], v[182:185], v[198:201], v[42:45]
	v_mfma_f32_16x16x32_bf16 v[30:33], v[170:173], v[206:209], v[30:33]
	v_mfma_f32_16x16x32_bf16 v[26:29], v[182:185], v[206:209], v[26:29]
	v_mfma_f32_16x16x32_bf16 v[14:17], v[170:173], v[214:217], v[14:17]
	v_mfma_f32_16x16x32_bf16 v[10:13], v[182:185], v[214:217], v[10:13]
	v_mfma_f32_16x16x32_bf16 v[62:65], v[174:177], v[194:197], v[62:65]
	v_mfma_f32_16x16x32_bf16 v[58:61], v[186:189], v[194:197], v[58:61]
	v_mfma_f32_16x16x32_bf16 v[46:49], v[174:177], v[202:205], v[46:49]
	v_mfma_f32_16x16x32_bf16 v[42:45], v[186:189], v[202:205], v[42:45]
	v_mfma_f32_16x16x32_bf16 v[30:33], v[174:177], v[210:213], v[30:33]
	v_mfma_f32_16x16x32_bf16 v[26:29], v[186:189], v[210:213], v[26:29]
	v_mfma_f32_16x16x32_bf16 v[14:17], v[174:177], v[218:221], v[14:17]
	v_mfma_f32_16x16x32_bf16 v[10:13], v[186:189], v[218:221], v[10:13]
	s_barrier
	s_add_u32 s94, s16, 0x40000
	s_addc_u32 s95, s17, 0
	s_add_i32 vcc_lo, vcc_lo, s5
	v_lshl_add_u64 v[170:171], s[94:95], 0, v[154:155]
	s_mov_b32 m0, vcc_lo
	s_nop 0
	global_load_lds_dwordx4 v[170:171], off
	v_lshl_add_u64 v[170:171], s[94:95], 0, v[138:139]
	s_add_i32 m0, vcc_lo, 0x2000
	s_nop 0
	global_load_lds_dwordx4 v[170:171], off
	s_waitcnt vmcnt(6)
	s_barrier
	v_mfma_f32_16x16x32_bf16 v[54:57], v[222:225], v[190:193], v[54:57]
	v_mfma_f32_16x16x32_bf16 v[50:53], v[230:233], v[190:193], v[50:53]
	v_mfma_f32_16x16x32_bf16 v[38:41], v[222:225], v[198:201], v[38:41]
	v_mfma_f32_16x16x32_bf16 v[34:37], v[230:233], v[198:201], v[34:37]
	v_mfma_f32_16x16x32_bf16 v[22:25], v[222:225], v[206:209], v[22:25]
	v_mfma_f32_16x16x32_bf16 v[18:21], v[230:233], v[206:209], v[18:21]
	v_mfma_f32_16x16x32_bf16 v[6:9], v[222:225], v[214:217], v[6:9]
	v_mfma_f32_16x16x32_bf16 v[2:5], v[230:233], v[214:217], v[2:5]
	v_mfma_f32_16x16x32_bf16 v[54:57], v[226:229], v[194:197], v[54:57]
	v_mfma_f32_16x16x32_bf16 v[50:53], v[234:237], v[194:197], v[50:53]
	v_mfma_f32_16x16x32_bf16 v[38:41], v[226:229], v[202:205], v[38:41]
	v_mfma_f32_16x16x32_bf16 v[34:37], v[234:237], v[202:205], v[34:37]
	v_mfma_f32_16x16x32_bf16 v[22:25], v[226:229], v[210:213], v[22:25]
	v_mfma_f32_16x16x32_bf16 v[18:21], v[234:237], v[210:213], v[18:21]
	v_mfma_f32_16x16x32_bf16 v[6:9], v[226:229], v[218:221], v[6:9]
	v_mfma_f32_16x16x32_bf16 v[2:5], v[234:237], v[218:221], v[2:5]
	s_add_i32 s94, 32, 0x18000
	v_add_u32_e32 v131, s94, v145
	s_barrier
	ds_read_b128 v[170:173], v131
	ds_read_b128 v[174:177], v131 offset:1024
	ds_read_b128 v[182:185], v131 offset:2048
	ds_read_b128 v[186:189], v131 offset:3072
	s_add_u32 s2, s2, 0x40000
	s_addc_u32 s3, s3, 0
	s_mov_b32 m0, s4
	v_lshl_add_u64 v[222:223], s[2:3], 0, v[134:135]
	ds_read_b128 v[190:193], v151 offset:32768
	ds_read_b128 v[194:197], v151 offset:33792
	ds_read_b128 v[198:201], v151 offset:34816
	ds_read_b128 v[202:205], v151 offset:35840
	ds_read_b128 v[206:209], v151 offset:36864
	ds_read_b128 v[210:213], v151 offset:37888
	ds_read_b128 v[214:217], v151 offset:38912
	ds_read_b128 v[218:221], v151 offset:39936
	global_load_lds_dwordx4 v[222:223], off
	v_lshl_add_u64 v[222:223], s[2:3], 0, v[136:137]
	s_mov_b32 m0, s20
	s_nop 0
	global_load_lds_dwordx4 v[222:223], off
	s_waitcnt lgkmcnt(8)
	s_barrier
	s_waitcnt lgkmcnt(0)
	s_waitcnt lgkmcnt(0)
	v_mfma_f32_16x16x32_bf16 v[126:129], v[170:173], v[190:193], v[126:129]
	v_mfma_f32_16x16x32_bf16 v[122:125], v[182:185], v[190:193], v[122:125]
	v_mfma_f32_16x16x32_bf16 v[110:113], v[170:173], v[198:201], v[110:113]
	v_mfma_f32_16x16x32_bf16 v[106:109], v[182:185], v[198:201], v[106:109]
	v_mfma_f32_16x16x32_bf16 v[94:97], v[170:173], v[206:209], v[94:97]
	v_mfma_f32_16x16x32_bf16 v[90:93], v[182:185], v[206:209], v[90:93]
	v_mfma_f32_16x16x32_bf16 v[78:81], v[170:173], v[214:217], v[78:81]
	v_mfma_f32_16x16x32_bf16 v[74:77], v[182:185], v[214:217], v[74:77]
	v_mfma_f32_16x16x32_bf16 v[126:129], v[174:177], v[194:197], v[126:129]
	v_mfma_f32_16x16x32_bf16 v[122:125], v[186:189], v[194:197], v[122:125]
	v_mfma_f32_16x16x32_bf16 v[110:113], v[174:177], v[202:205], v[110:113]
	v_mfma_f32_16x16x32_bf16 v[106:109], v[186:189], v[202:205], v[106:109]
	v_mfma_f32_16x16x32_bf16 v[94:97], v[174:177], v[210:213], v[94:97]
	v_mfma_f32_16x16x32_bf16 v[90:93], v[186:189], v[210:213], v[90:93]
	v_mfma_f32_16x16x32_bf16 v[78:81], v[174:177], v[218:221], v[78:81]
	v_mfma_f32_16x16x32_bf16 v[74:77], v[186:189], v[218:221], v[74:77]
	s_barrier
	s_add_i32 s95, 32, 0x1c000
	s_add_i32 s2, s94, s5
	v_add_u32_e32 v131, s95, v145
	v_lshl_add_u64 v[132:133], v[132:133], 0, s[44:45]
	s_mov_b32 m0, s2
	ds_read_b128 v[222:225], v131
	ds_read_b128 v[226:229], v131 offset:1024
	ds_read_b128 v[230:233], v131 offset:2048
	ds_read_b128 v[234:237], v131 offset:3072
	global_load_lds_dwordx4 v[132:133], off
	v_lshl_add_u64 v[132:133], v[178:179], 0, s[44:45]
	s_add_i32 m0, s2, 0x2000
	s_nop 0
	global_load_lds_dwordx4 v[132:133], off
	s_barrier
	s_waitcnt lgkmcnt(0)
	s_waitcnt lgkmcnt(0)
	v_mfma_f32_16x16x32_bf16 v[118:121], v[222:225], v[190:193], v[118:121]
	v_mfma_f32_16x16x32_bf16 v[114:117], v[230:233], v[190:193], v[114:117]
	v_mfma_f32_16x16x32_bf16 v[102:105], v[222:225], v[198:201], v[102:105]
	v_mfma_f32_16x16x32_bf16 v[98:101], v[230:233], v[198:201], v[98:101]
	v_mfma_f32_16x16x32_bf16 v[86:89], v[222:225], v[206:209], v[86:89]
	v_mfma_f32_16x16x32_bf16 v[82:85], v[230:233], v[206:209], v[82:85]
	v_mfma_f32_16x16x32_bf16 v[70:73], v[222:225], v[214:217], v[70:73]
	v_mfma_f32_16x16x32_bf16 v[66:69], v[230:233], v[214:217], v[66:69]
	v_mfma_f32_16x16x32_bf16 v[118:121], v[226:229], v[194:197], v[118:121]
	v_mfma_f32_16x16x32_bf16 v[114:117], v[234:237], v[194:197], v[114:117]
	v_mfma_f32_16x16x32_bf16 v[102:105], v[226:229], v[202:205], v[102:105]
	v_mfma_f32_16x16x32_bf16 v[98:101], v[234:237], v[202:205], v[98:101]
	v_mfma_f32_16x16x32_bf16 v[86:89], v[226:229], v[210:213], v[86:89]
	v_mfma_f32_16x16x32_bf16 v[82:85], v[234:237], v[210:213], v[82:85]
	v_mfma_f32_16x16x32_bf16 v[70:73], v[226:229], v[218:221], v[70:73]
	v_mfma_f32_16x16x32_bf16 v[66:69], v[234:237], v[218:221], v[66:69]
	s_mov_b32 m0, s21
	v_lshl_add_u64 v[132:133], v[238:239], 0, s[44:45]
	s_barrier
	ds_read_b128 v[190:193], v151 offset:49152
	ds_read_b128 v[194:197], v151 offset:50176
	ds_read_b128 v[198:201], v151 offset:51200
	ds_read_b128 v[202:205], v151 offset:52224
	ds_read_b128 v[206:209], v151 offset:53248
	ds_read_b128 v[210:213], v151 offset:54272
	ds_read_b128 v[214:217], v151 offset:55296
	ds_read_b128 v[218:221], v151 offset:56320
	global_load_lds_dwordx4 v[132:133], off
	v_lshl_add_u64 v[132:133], v[240:241], 0, s[44:45]
	s_mov_b32 m0, s22
	s_nop 0
	global_load_lds_dwordx4 v[132:133], off
	s_barrier
	s_waitcnt lgkmcnt(0)
	s_waitcnt lgkmcnt(0)
	v_mfma_f32_16x16x32_bf16 v[62:65], v[170:173], v[190:193], v[62:65]
	v_mfma_f32_16x16x32_bf16 v[58:61], v[182:185], v[190:193], v[58:61]
	v_mfma_f32_16x16x32_bf16 v[46:49], v[170:173], v[198:201], v[46:49]
	v_mfma_f32_16x16x32_bf16 v[42:45], v[182:185], v[198:201], v[42:45]
	v_mfma_f32_16x16x32_bf16 v[30:33], v[170:173], v[206:209], v[30:33]
	v_mfma_f32_16x16x32_bf16 v[26:29], v[182:185], v[206:209], v[26:29]
	v_mfma_f32_16x16x32_bf16 v[14:17], v[170:173], v[214:217], v[14:17]
	v_mfma_f32_16x16x32_bf16 v[10:13], v[182:185], v[214:217], v[10:13]
	v_mfma_f32_16x16x32_bf16 v[62:65], v[174:177], v[194:197], v[62:65]
	v_mfma_f32_16x16x32_bf16 v[58:61], v[186:189], v[194:197], v[58:61]
	v_mfma_f32_16x16x32_bf16 v[46:49], v[174:177], v[202:205], v[46:49]
	v_mfma_f32_16x16x32_bf16 v[42:45], v[186:189], v[202:205], v[42:45]
	v_mfma_f32_16x16x32_bf16 v[30:33], v[174:177], v[210:213], v[30:33]
	v_mfma_f32_16x16x32_bf16 v[26:29], v[186:189], v[210:213], v[26:29]
	v_mfma_f32_16x16x32_bf16 v[14:17], v[174:177], v[218:221], v[14:17]
	v_mfma_f32_16x16x32_bf16 v[10:13], v[186:189], v[218:221], v[10:13]
	s_barrier
	s_add_u32 s2, s16, 0x40080
	s_addc_u32 s3, s17, 0
	s_add_i32 s16, s95, s5
	v_lshl_add_u64 v[132:133], s[2:3], 0, v[154:155]
	s_mov_b32 m0, s16
	s_nop 0
	global_load_lds_dwordx4 v[132:133], off
	v_lshl_add_u64 v[132:133], s[2:3], 0, v[138:139]
	s_add_i32 m0, s16, 0x2000
	s_nop 0
	global_load_lds_dwordx4 v[132:133], off
	s_waitcnt vmcnt(6)
	s_barrier
	v_mfma_f32_16x16x32_bf16 v[54:57], v[222:225], v[190:193], v[54:57]
	v_mfma_f32_16x16x32_bf16 v[50:53], v[230:233], v[190:193], v[50:53]
	v_mfma_f32_16x16x32_bf16 v[38:41], v[222:225], v[198:201], v[38:41]
	v_mfma_f32_16x16x32_bf16 v[34:37], v[230:233], v[198:201], v[34:37]
	v_mfma_f32_16x16x32_bf16 v[22:25], v[222:225], v[206:209], v[22:25]
	v_mfma_f32_16x16x32_bf16 v[18:21], v[230:233], v[206:209], v[18:21]
	v_mfma_f32_16x16x32_bf16 v[6:9], v[222:225], v[214:217], v[6:9]
	v_mfma_f32_16x16x32_bf16 v[2:5], v[230:233], v[214:217], v[2:5]
	v_mfma_f32_16x16x32_bf16 v[54:57], v[226:229], v[194:197], v[54:57]
	v_mfma_f32_16x16x32_bf16 v[50:53], v[234:237], v[194:197], v[50:53]
	v_mfma_f32_16x16x32_bf16 v[38:41], v[226:229], v[202:205], v[38:41]
	v_mfma_f32_16x16x32_bf16 v[34:37], v[234:237], v[202:205], v[34:37]
	v_mfma_f32_16x16x32_bf16 v[22:25], v[226:229], v[210:213], v[22:25]
	v_mfma_f32_16x16x32_bf16 v[18:21], v[234:237], v[210:213], v[18:21]
	v_mfma_f32_16x16x32_bf16 v[6:9], v[226:229], v[218:221], v[6:9]
	v_mfma_f32_16x16x32_bf16 v[2:5], v[234:237], v[218:221], v[2:5]
	s_add_i32 s39, s39, 2
	s_add_u32 s30, s30, 0x100
	s_addc_u32 s31, s31, 0
	s_add_u32 s28, s28, 0x100
	s_addc_u32 s29, s29, 0
	s_cmp_gt_u32 s39, 13
	s_barrier
	s_cbranch_scc0 .LBB0_620
	s_cmp_gt_i32 s10, 2
	s_cselect_b64 s[94:95], -1, 0
	s_mov_b64 s[28:29], -1
	s_and_b64 vcc, exec, s[94:95]
	s_cbranch_vccz .LBB0_638
	s_cmp_gt_u32 s10, 5
	s_mov_b64 s[30:31], -1
	s_cbranch_scc0 .LBB0_636
	s_cmp_gt_u32 s10, 8
	s_cbranch_scc0 .LBB0_633
	s_cmp_gt_u32 s10, 10
	s_mov_b64 s[2:3], -1
	s_cbranch_scc0 .LBB0_631
	s_cmp_lt_i32 s10, 12
	s_mov_b64 s[2:3], 0
	s_cbranch_scc1 .LBB0_630
	s_cmp_lg_u32 s10, 12
	s_mov_b64 s[16:17], -1
	s_cbranch_scc0 .LBB0_628
	s_mov_b64 s[16:17], 0

.LBB0_640:
	s_waitcnt vmcnt(6)
	v_fmamk_f32 v130, v130, 0x3a800000, v1
	v_cmp_gt_f32_e32 vcc, s33, v130
	v_mul_f32_e32 v131, 0x4b800000, v130
	s_mov_b64 s[10:11], -1
	v_cndmask_b32_e32 v130, v130, v131, vcc
	v_rsq_f32_e32 v130, v130
	v_lshl_add_u32 v169, s34, 8, v144
	v_readlane_b32 s28, v242, 45
	v_readlane_b32 s29, v242, 46
	v_mul_f32_e32 v131, 0x45800000, v130
	v_cndmask_b32_e32 v170, v130, v131, vcc
	v_mul_f32_e32 v126, v170, v126
	v_mul_f32_e32 v122, v170, v122
	s_andn2_b64 vcc, exec, s[2:3]
	s_cbranch_vccz .LBB0_650
	s_xor_b64 s[10:11], s[18:19], -1
	s_mov_b64 s[2:3], -1
	s_and_b64 vcc, exec, s[10:11]
	s_cbranch_vccz .LBB0_647
	s_xor_b64 s[10:11], s[16:17], -1
	s_and_b64 vcc, exec, s[10:11]
	s_cbranch_vccz .LBB0_644
	v_mul_f32_e32 v130, v170, v127
	v_mul_f32_e32 v131, v170, v128
	v_mul_f32_e32 v171, v170, v129
	v_cvt_pk_bf16_f32 v130, v126, v130
	v_cvt_pk_bf16_f32 v131, v131, v171
	v_fmamk_f32 v171, v168, 0x3a800000, v1
	v_mul_f32_e32 v175, 0x4b800000, v171
	v_cmp_gt_f32_e32 vcc, s33, v171
	v_lshlrev_b32_e32 v173, 11, v169
	v_or_b32_e32 v174, v173, v146
	v_cndmask_b32_e32 v171, v171, v175, vcc
	v_rsq_f32_e32 v171, v171
	v_mul_f32_e32 v132, v170, v123
	v_mul_f32_e32 v133, v170, v124
	v_add_lshl_u32 v174, s13, v174, 1
	v_mul_f32_e32 v172, v170, v125
	v_cvt_pk_bf16_f32 v132, v122, v132
	v_cvt_pk_bf16_f32 v133, v133, v172
	buffer_store_dwordx4 v[130:133], v174, s[72:75], 0 offen sc1
	v_add_u32_e32 v178, 0x10000, v174
	s_mov_b64 s[2:3], 0
	v_mul_f32_e32 v130, 0x45800000, v171
	v_cndmask_b32_e32 v130, v171, v130, vcc
	v_mul_f32_e32 v133, v130, v111
	v_mul_f32_e32 v131, v130, v110
	v_mul_f32_e32 v132, v130, v106
	v_mul_f32_e32 v171, v130, v107
	v_mul_f32_e32 v172, v130, v112
	v_mul_f32_e32 v175, v130, v108
	v_mul_f32_e32 v176, v130, v113
	v_mul_f32_e32 v177, v130, v109
	v_cvt_pk_bf16_f32 v130, v131, v133
	v_fmamk_f32 v133, v167, 0x3a800000, v1
	v_cvt_pk_bf16_f32 v131, v172, v176
	v_mul_f32_e32 v172, 0x4b800000, v133
	v_cmp_gt_f32_e32 vcc, s33, v133
	v_cvt_pk_bf16_f32 v132, v132, v171
	s_nop 1
	v_cndmask_b32_e32 v133, v133, v172, vcc
	v_rsq_f32_e32 v172, v133
	v_cvt_pk_bf16_f32 v133, v175, v177
	buffer_store_dwordx4 v[130:133], v178, s[72:75], 0 offen sc1
	v_add_u32_e32 v178, 0x20000, v174
	v_add_u32_e32 v174, 0x30000, v174
	v_mul_f32_e32 v130, 0x45800000, v172
	v_cndmask_b32_e32 v130, v172, v130, vcc
	v_mul_f32_e32 v133, v130, v95
	v_mul_f32_e32 v131, v130, v94
	v_mul_f32_e32 v132, v130, v90
	v_mul_f32_e32 v171, v130, v91
	v_mul_f32_e32 v172, v130, v96
	v_mul_f32_e32 v175, v130, v92
	v_mul_f32_e32 v176, v130, v97
	v_mul_f32_e32 v177, v130, v93
	v_cvt_pk_bf16_f32 v130, v131, v133
	v_fmamk_f32 v133, v166, 0x3a800000, v1
	v_cvt_pk_bf16_f32 v131, v172, v176
	v_mul_f32_e32 v172, 0x4b800000, v133
	v_cmp_gt_f32_e32 vcc, s33, v133
	v_cvt_pk_bf16_f32 v132, v132, v171
	s_nop 1
	v_cndmask_b32_e32 v133, v133, v172, vcc
	v_rsq_f32_e32 v172, v133
	v_cvt_pk_bf16_f32 v133, v175, v177
	buffer_store_dwordx4 v[130:133], v178, s[72:75], 0 offen sc1
	s_nop 1
	v_mul_f32_e32 v130, 0x45800000, v172
	v_cndmask_b32_e32 v130, v172, v130, vcc
	v_mul_f32_e32 v133, v130, v79
	v_mul_f32_e32 v131, v130, v78
	v_mul_f32_e32 v132, v130, v74
	v_mul_f32_e32 v171, v130, v75
	v_mul_f32_e32 v172, v130, v80
	v_mul_f32_e32 v175, v130, v76
	v_mul_f32_e32 v176, v130, v81
	v_mul_f32_e32 v177, v130, v77
	v_cvt_pk_bf16_f32 v130, v131, v133
	v_fmamk_f32 v133, v165, 0x3a800000, v1
	v_cvt_pk_bf16_f32 v131, v172, v176
	v_mul_f32_e32 v172, 0x4b800000, v133
	v_cmp_gt_f32_e32 vcc, s33, v133
	v_cvt_pk_bf16_f32 v132, v132, v171
	s_nop 1
	v_cndmask_b32_e32 v133, v133, v172, vcc
	v_rsq_f32_e32 v172, v133
	v_cvt_pk_bf16_f32 v133, v175, v177
	buffer_store_dwordx4 v[130:133], v174, s[72:75], 0 offen sc1
	s_nop 1
	v_mul_f32_e32 v130, 0x45800000, v172
	v_cndmask_b32_e32 v130, v172, v130, vcc
	v_mul_f32_e32 v131, v130, v62
	v_mul_f32_e32 v132, v130, v58
	v_mul_f32_e32 v133, v130, v63
	v_mul_f32_e32 v171, v130, v59
	v_mul_f32_e32 v172, v130, v64
	v_mul_f32_e32 v174, v130, v60
	v_mul_f32_e32 v175, v130, v65
	v_mul_f32_e32 v176, v130, v61
	v_add_u32_e32 v130, v173, v147
	v_add_lshl_u32 v177, v130, s13, 1
	v_cvt_pk_bf16_f32 v130, v131, v133
	v_fmamk_f32 v133, v164, 0x3a800000, v1
	v_cvt_pk_bf16_f32 v131, v172, v175
	v_mul_f32_e32 v172, 0x4b800000, v133
	v_cmp_gt_f32_e32 vcc, s33, v133
	v_cvt_pk_bf16_f32 v132, v132, v171
	s_nop 1
	v_cndmask_b32_e32 v133, v133, v172, vcc
	v_rsq_f32_e32 v172, v133
	v_cvt_pk_bf16_f32 v133, v174, v176
	buffer_store_dwordx4 v[130:133], v177, s[72:75], 0 offen sc1
	s_nop 1
	v_mul_f32_e32 v130, 0x45800000, v172
	v_cndmask_b32_e32 v130, v172, v130, vcc
	v_mul_f32_e32 v131, v130, v46
	v_mul_f32_e32 v132, v130, v42
	v_mul_f32_e32 v133, v130, v47
	v_mul_f32_e32 v171, v130, v43
	v_mul_f32_e32 v172, v130, v48
	v_mul_f32_e32 v174, v130, v44
	v_mul_f32_e32 v175, v130, v49
	v_mul_f32_e32 v176, v130, v45
	v_add_u32_e32 v130, v173, v148
	v_add_lshl_u32 v177, v130, s13, 1
	v_cvt_pk_bf16_f32 v130, v131, v133
	v_fmamk_f32 v133, v153, 0x3a800000, v1
	v_cvt_pk_bf16_f32 v131, v172, v175
	v_mul_f32_e32 v172, 0x4b800000, v133
	v_cmp_gt_f32_e32 vcc, s33, v133
	v_cvt_pk_bf16_f32 v132, v132, v171
	s_nop 1
	v_cndmask_b32_e32 v133, v133, v172, vcc
	v_rsq_f32_e32 v172, v133
	v_cvt_pk_bf16_f32 v133, v174, v176
	buffer_store_dwordx4 v[130:133], v177, s[72:75], 0 offen sc1
	s_nop 1
	v_mul_f32_e32 v130, 0x45800000, v172
	v_cndmask_b32_e32 v130, v172, v130, vcc
	v_mul_f32_e32 v131, v130, v30
	v_mul_f32_e32 v132, v130, v26
	v_mul_f32_e32 v133, v130, v31
	v_mul_f32_e32 v171, v130, v27
	v_mul_f32_e32 v172, v130, v32
	v_mul_f32_e32 v174, v130, v28
	v_mul_f32_e32 v175, v130, v33
	v_mul_f32_e32 v176, v130, v29
	v_add_u32_e32 v130, v173, v149
	v_add_lshl_u32 v177, v130, s13, 1
	v_cvt_pk_bf16_f32 v130, v131, v133
	v_fmamk_f32 v133, v152, 0x3a800000, v1
	v_cvt_pk_bf16_f32 v131, v172, v175
	v_mul_f32_e32 v172, 0x4b800000, v133
	v_cmp_gt_f32_e32 vcc, s33, v133
	v_cvt_pk_bf16_f32 v132, v132, v171
	s_nop 1
	v_cndmask_b32_e32 v133, v133, v172, vcc
	v_rsq_f32_e32 v172, v133
	v_cvt_pk_bf16_f32 v133, v174, v176
	buffer_store_dwordx4 v[130:133], v177, s[72:75], 0 offen sc1
	v_add3_u32 v174, v173, v150, s13
	s_nop 0
	v_mul_f32_e32 v130, 0x45800000, v172
	v_cndmask_b32_e32 v130, v172, v130, vcc
	v_mul_f32_e32 v131, v130, v14
	v_mul_f32_e32 v132, v130, v10
	v_mul_f32_e32 v133, v130, v15
	v_mul_f32_e32 v171, v130, v11
	v_mul_f32_e32 v172, v130, v16
	v_mul_f32_e32 v175, v130, v12
	v_mul_f32_e32 v176, v130, v17
	v_mul_f32_e32 v177, v130, v13
	v_cvt_pk_bf16_f32 v130, v131, v133
	v_cvt_pk_bf16_f32 v131, v172, v176
	v_cvt_pk_bf16_f32 v132, v132, v171
	v_cvt_pk_bf16_f32 v133, v175, v177

.LBB0_662:
	s_setprio 0
	s_waitcnt vmcnt(0)
	v_readlane_b32 s0, v242, 51
	s_cmpk_gt_u32 s0, 0xff
	v_readlane_b32 s20, v242, 43
	v_readlane_b32 s21, v242, 44
	s_cbranch_scc1 .LBB0_664
	s_barrier

.LBB0_697:
	s_andn2_saveexec_b64 s[2:3], s[2:3]
	s_cbranch_execz .LBB0_717
	s_mov_b64 s[2:3], exec
	s_waitcnt lgkmcnt(0)
	s_waitcnt vmcnt(0)
	v_mbcnt_lo_u32_b32 v3, s2, 0
	v_mbcnt_hi_u32_b32 v3, s3, v3
	v_cmp_eq_u32_e32 vcc, 0, v3
	s_and_saveexec_b64 s[10:11], vcc
	s_cbranch_execz .LBB0_700
	s_bcnt1_i32_b64 s2, s[2:3]
	v_mov_b32_e32 v4, s2
	v_readlane_b32 s2, v243, 14
	v_readlane_b32 s3, v243, 15
	s_nop 4
	global_atomic_add v4, v155, v4, s[2:3] sc0

.LBB0_921:
	s_and_b32 s3, s5, 0x3c0
	v_or_b32_e32 v2, s3, v43
	v_lshlrev_b32_e32 v154, 11, v2
	s_and_b32 s2, s4, 0xffffffe0
	v_lshl_add_u64 v[60:61], v[38:39], 0, v[154:155]
	v_add_u32_e32 v40, s2, v42
	v_ashrrev_i32_e32 v41, 31, v40
	v_lshlrev_b64 v[62:63], 11, v[40:41]
	v_lshl_add_u64 v[64:65], v[36:37], 0, v[62:63]
	s_mov_b32 s2, 0x10000
	v_add_co_u32_e32 v66, vcc, s2, v60
	s_mov_b32 s2, 0x7060302
	s_nop 0
	v_addc_co_u32_e32 v67, vcc, 0, v61, vcc
	global_load_dwordx4 v[68:71], v[60:61], off
	global_load_dwordx4 v[100:103], v[64:65], off
	global_load_dwordx4 v[182:185], v[66:67], off
	global_load_dwordx4 v[72:75], v[60:61], off offset:32
	global_load_dwordx4 v[104:107], v[64:65], off offset:32
	global_load_dwordx4 v[186:189], v[66:67], off offset:32
	global_load_dwordx4 v[76:79], v[60:61], off offset:64
	global_load_dwordx4 v[108:111], v[64:65], off offset:64
	global_load_dwordx4 v[190:193], v[66:67], off offset:64
	global_load_dwordx4 v[80:83], v[60:61], off offset:96
	global_load_dwordx4 v[112:115], v[64:65], off offset:96
	global_load_dwordx4 v[194:197], v[66:67], off offset:96
	global_load_dwordx4 v[84:87], v[60:61], off offset:128
	global_load_dwordx4 v[116:119], v[64:65], off offset:128
	global_load_dwordx4 v[198:201], v[66:67], off offset:128
	global_load_dwordx4 v[88:91], v[60:61], off offset:160
	global_load_dwordx4 v[120:123], v[64:65], off offset:160
	global_load_dwordx4 v[202:205], v[66:67], off offset:160
	global_load_dwordx4 v[92:95], v[60:61], off offset:192
	global_load_dwordx4 v[124:127], v[64:65], off offset:192
	global_load_dwordx4 v[206:209], v[66:67], off offset:192
	global_load_dwordx4 v[96:99], v[60:61], off offset:224
	global_load_dwordx4 v[128:131], v[64:65], off offset:224
	global_load_dwordx4 v[210:213], v[66:67], off offset:224
	v_lshl_add_u64 v[60:61], s[58:59], 0, v[62:63]
	v_add_u32_e32 v56, s3, v44
	v_or_b32_e32 v58, v56, v34
	v_ashrrev_i32_e32 v59, 31, v58
	v_lshl_add_u64 v[58:59], v[58:59], 1, v[60:61]
	v_ashrrev_i32_e32 v57, 31, v56
	v_lshl_add_u64 v[216:217], v[56:57], 0, v[34:35]
	v_lshl_add_u64 v[216:217], v[216:217], 1, v[60:61]
	global_load_dword v214, v[58:59], off
	global_load_dword v215, v[216:217], off offset:64
	s_waitcnt vmcnt(23)
	v_mfma_f32_32x32x16_bf16 v[2:17], v[68:71], v[100:103], 0
	v_mfma_f32_32x32x16_bf16 v[18:33], v[182:185], v[100:103], 0
	s_waitcnt vmcnt(20)
	v_mfma_f32_32x32x16_bf16 v[2:17], v[72:75], v[104:107], v[2:17]
	v_mfma_f32_32x32x16_bf16 v[18:33], v[186:189], v[104:107], v[18:33]
	s_waitcnt vmcnt(17)
	v_mfma_f32_32x32x16_bf16 v[2:17], v[76:79], v[108:111], v[2:17]
	v_mfma_f32_32x32x16_bf16 v[18:33], v[190:193], v[108:111], v[18:33]
	s_waitcnt vmcnt(14)
	v_mfma_f32_32x32x16_bf16 v[2:17], v[80:83], v[112:115], v[2:17]
	v_mfma_f32_32x32x16_bf16 v[18:33], v[194:197], v[112:115], v[18:33]
	s_waitcnt vmcnt(11)
	v_mfma_f32_32x32x16_bf16 v[2:17], v[84:87], v[116:119], v[2:17]
	v_mfma_f32_32x32x16_bf16 v[18:33], v[198:201], v[116:119], v[18:33]
	s_waitcnt vmcnt(8)
	v_mfma_f32_32x32x16_bf16 v[2:17], v[88:91], v[120:123], v[2:17]
	v_mfma_f32_32x32x16_bf16 v[18:33], v[202:205], v[120:123], v[18:33]
	s_waitcnt vmcnt(5)
	v_mfma_f32_32x32x16_bf16 v[2:17], v[92:95], v[124:127], v[2:17]
	v_mfma_f32_32x32x16_bf16 v[18:33], v[206:209], v[124:127], v[18:33]
	s_waitcnt vmcnt(2)
	v_mfma_f32_32x32x16_bf16 v[2:17], v[96:99], v[128:131], v[2:17]
	v_mfma_f32_32x32x16_bf16 v[18:33], v[210:213], v[128:131], v[18:33]
	s_nop 7
	s_nop 4
	ds_write2st64_b32 v46, v2, v3 offset1:1
	ds_write2st64_b32 v46, v4, v5 offset0:2 offset1:3
	ds_write2st64_b32 v46, v6, v7 offset0:4 offset1:5
	ds_write2st64_b32 v46, v8, v9 offset0:6 offset1:7
	ds_write2st64_b32 v46, v10, v11 offset0:8 offset1:9
	ds_write2st64_b32 v46, v12, v13 offset0:10 offset1:11
	ds_write2st64_b32 v46, v14, v15 offset0:12 offset1:13
	ds_write2st64_b32 v46, v16, v17 offset0:14 offset1:15
	ds_write2st64_b32 v46, v18, v19 offset0:16 offset1:17
	ds_write2st64_b32 v46, v20, v21 offset0:18 offset1:19
	ds_write2st64_b32 v46, v22, v23 offset0:20 offset1:21
	ds_write2st64_b32 v46, v24, v25 offset0:22 offset1:23
	ds_write2st64_b32 v46, v26, v27 offset0:24 offset1:25
	ds_write2st64_b32 v46, v28, v29 offset0:26 offset1:27
	ds_write2st64_b32 v46, v30, v31 offset0:28 offset1:29
	ds_write2st64_b32 v46, v32, v33 offset0:30 offset1:31
	s_waitcnt lgkmcnt(0)
	s_barrier
	v_lshl_add_u64 v[2:3], v[56:57], 0, v[34:35]
	v_lshl_add_u64 v[4:5], v[2:3], 1, v[60:61]
	ds_read2st64_b32 v[2:3], v47 offset1:1
	ds_read2st64_b32 v[6:7], v47 offset0:32 offset1:33
	ds_read2st64_b32 v[8:9], v47 offset0:64 offset1:65
	ds_read2st64_b32 v[10:11], v47 offset0:96 offset1:97
	ds_read2st64_b32 v[12:13], v47 offset0:128 offset1:129
	ds_read2st64_b32 v[14:15], v47 offset0:160 offset1:161
	ds_read2st64_b32 v[16:17], v47 offset0:192 offset1:193
	ds_read2st64_b32 v[18:19], v47 offset0:224 offset1:225
	s_waitcnt lgkmcnt(7)
	v_pk_add_f32 v[2:3], v[2:3], 0 op_sel_hi:[1,0]
	s_waitcnt lgkmcnt(6)
	v_pk_add_f32 v[2:3], v[2:3], v[6:7]
	s_waitcnt vmcnt(0)
	v_and_b32_e32 v7, 0xffff0000, v214
	s_waitcnt lgkmcnt(5)
	v_pk_add_f32 v[2:3], v[2:3], v[8:9]
	v_lshlrev_b32_e32 v6, 16, v214
	s_waitcnt lgkmcnt(4)
	v_pk_add_f32 v[2:3], v[2:3], v[10:11]
	s_waitcnt lgkmcnt(3)
	v_pk_add_f32 v[2:3], v[2:3], v[12:13]
	s_waitcnt lgkmcnt(2)
	v_pk_add_f32 v[2:3], v[2:3], v[14:15]
	s_waitcnt lgkmcnt(1)
	v_pk_add_f32 v[2:3], v[2:3], v[16:17]
	s_waitcnt lgkmcnt(0)
	v_pk_add_f32 v[2:3], v[2:3], v[18:19]
	s_nop 0
	v_pk_add_f32 v[2:3], v[2:3], v[6:7]
	s_nop 0
	v_and_b32_sdwa v6, v3, v180 dst_sel:DWORD dst_unused:UNUSED_PAD src0_sel:WORD_1 src1_sel:DWORD
	v_and_b32_sdwa v7, v2, v180 dst_sel:DWORD dst_unused:UNUSED_PAD src0_sel:WORD_1 src1_sel:DWORD
	v_add3_u32 v7, v2, v7, s15
	v_add3_u32 v6, v3, v6, s15
	v_perm_b32 v6, v6, v7, s2
	global_store_dword v[58:59], v6, off sc1
	ds_read2st64_b32 v[6:7], v47 offset0:48 offset1:49
	ds_read2st64_b32 v[8:9], v47 offset0:16 offset1:17
	ds_read2st64_b32 v[10:11], v47 offset0:112 offset1:113
	ds_read2st64_b32 v[12:13], v47 offset0:80 offset1:81
	ds_read2st64_b32 v[14:15], v47 offset0:176 offset1:177
	ds_read2st64_b32 v[16:17], v47 offset0:144 offset1:145
	ds_read2st64_b32 v[18:19], v47 offset0:240 offset1:241
	ds_read2st64_b32 v[20:21], v47 offset0:208 offset1:209
	s_waitcnt lgkmcnt(6)
	v_pk_add_f32 v[8:9], v[8:9], 0 op_sel_hi:[1,0]
	v_pk_mul_f32 v[2:3], v[2:3], v[2:3]
	v_pk_add_f32 v[6:7], v[8:9], v[6:7]
	v_add_f32_e32 v8, v2, v3
	s_waitcnt lgkmcnt(4)
	v_pk_add_f32 v[6:7], v[6:7], v[12:13]
	v_and_b32_e32 v3, 0xffff0000, v215
	v_pk_add_f32 v[6:7], v[6:7], v[10:11]
	v_lshlrev_b32_e32 v2, 16, v215
	s_waitcnt lgkmcnt(2)
	v_pk_add_f32 v[6:7], v[6:7], v[16:17]
	s_nop 0
	v_pk_add_f32 v[6:7], v[6:7], v[14:15]
	s_waitcnt lgkmcnt(0)
	v_pk_add_f32 v[6:7], v[6:7], v[20:21]
	s_nop 0
	v_pk_add_f32 v[6:7], v[6:7], v[18:19]
	s_nop 0
	v_pk_add_f32 v[6:7], v[6:7], v[2:3]
	s_nop 0
	v_pk_mul_f32 v[2:3], v[6:7], v[6:7]
	v_and_b32_sdwa v9, v7, v180 dst_sel:DWORD dst_unused:UNUSED_PAD src0_sel:WORD_1 src1_sel:DWORD
	v_add_f32_e32 v2, v8, v2
	v_add_f32_e32 v2, v2, v3
	ds_bpermute_b32 v3, v45, v2
	v_and_b32_sdwa v8, v6, v180 dst_sel:DWORD dst_unused:UNUSED_PAD src0_sel:WORD_1 src1_sel:DWORD
	v_add3_u32 v6, v6, v8, s15
	v_add3_u32 v7, v7, v9, s15
	v_perm_b32 v6, v7, v6, s2
	global_store_dword v[4:5], v6, off offset:64 sc1
	s_and_saveexec_b64 s[2:3], s[40:41]
	s_cbranch_execz .LBB0_920
	v_lshl_add_u64 v[4:5], v[40:41], 2, s[0:1]
	s_waitcnt lgkmcnt(0)
	v_add_f32_e32 v2, v2, v3
	global_atomic_add_f32 v[4:5], v2, off
	s_branch .LBB0_920
.LBB0_923:
	v_readlane_b32 s0, v242, 0
	v_readlane_b32 s1, v242, 1
	s_lshl_b64 s[0:1], s[0:1], 2
	v_readlane_b32 s4, v244, 0
	v_readlane_b32 s5, v244, 1
	s_add_u32 s0, s4, s0
	s_addc_u32 s1, s5, s1
	s_add_u32 s0, s0, 0x10800
	v_mov_b32_e32 v8, v0
	s_addc_u32 s1, s1, 0
	s_and_b64 vcc, exec, s[16:17]
	v_readfirstlane_b32 s4, v8
	v_readlane_b32 s6, v244, 2
	v_readlane_b32 s7, v244, 3
	s_cbranch_vccnz .LBB0_955
	v_lshlrev_b32_e32 v5, 4, v8
	v_add_u32_e32 v3, 0x2000, v5
	v_ashrrev_i32_e32 v2, 31, v3
	v_lshrrev_b32_e32 v2, 22, v2
	v_add_u32_e32 v2, v3, v2
	v_ashrrev_i32_e32 v2, 10, v2
	v_mul_i32_i24_e32 v4, 0x400, v2
	v_sub_u32_e32 v3, v3, v4
	v_writelane_b32 v242, s16, 53
	v_lshrrev_b32_e32 v4, 4, v3
	v_bitop3_b32 v4, v4, v3, 32 bitop3:0x6c
	v_writelane_b32 v242, s17, 54
	v_writelane_b32 v242, s12, 51
	v_ashrrev_i32_e32 v3, 31, v4
	v_lshrrev_b32_e32 v3, 26, v3
	v_writelane_b32 v242, s13, 52
	v_add_u32_e32 v6, v4, v3
	v_readlane_b32 s2, v242, 40
	v_lshlrev_b32_e32 v7, 3, v2
	s_lshl_b32 s2, s2, 21
	v_ashrrev_i32_e32 v3, 6, v6
	v_and_b32_e32 v7, -16, v7
	s_add_u32 s5, s54, s2
	v_add_u32_e32 v7, v3, v7
	s_addc_u32 s6, s55, 0
	s_ashr_i32 s3, s4, 8
	v_writelane_b32 v242, s4, 55
	s_ashr_i32 s2, s4, 6
	v_and_b32_e32 v9, 3, v3
	s_mov_b32 s4, 0x1fffe0
	v_lshrrev_b32_e32 v10, 2, v7
	v_lshlrev_b32_e32 v11, 1, v7
	v_and_b32_e32 v6, 0xc0, v6
	v_and_or_b32 v9, v7, s4, v9
	v_and_b32_e32 v10, 4, v10
	v_and_b32_e32 v11, 24, v11
	v_sub_u32_e32 v4, v4, v6
	v_or3_b32 v9, v9, v10, v11
	v_lshlrev_b32_e32 v10, 5, v2
	v_ashrrev_i16_sdwa v4, v180, sext(v4) dst_sel:DWORD dst_unused:UNUSED_PAD src0_sel:DWORD src1_sel:BYTE_0
	v_and_b32_e32 v10, 32, v10
	v_bfe_i32 v4, v4, 0, 16
	v_add_lshl_u32 v6, v10, v4, 1
	v_lshl_add_u32 v130, v9, 11, v6
	v_lshl_add_u32 v132, v7, 11, v6
	v_bfe_i32 v6, v8, 27, 1
	v_lshrrev_b32_e32 v6, 22, v6
	v_add_u32_e32 v6, v5, v6
	v_and_b32_e32 v6, 0xfffffc00, v6
	v_sub_u32_e32 v5, v5, v6
	v_lshrrev_b32_e32 v6, 4, v5
	v_bitop3_b32 v7, v6, v5, 32 bitop3:0x6c
	v_ashrrev_i32_e32 v6, 31, v8
	v_lshrrev_b32_e32 v6, 26, v6
	v_ashrrev_i32_e32 v5, 31, v5
	v_add_u32_e32 v6, v8, v6
	v_lshrrev_b32_e32 v5, 26, v5
	v_ashrrev_i32_e32 v6, 6, v6
	v_add_u32_e32 v5, v7, v5
	v_lshlrev_b32_e32 v9, 3, v6
	v_ashrrev_i32_e32 v5, 6, v5
	v_and_b32_e32 v9, -16, v9
	v_add_u32_e32 v9, v5, v9
	v_and_b32_e32 v10, 3, v5
	v_lshrrev_b32_e32 v11, 2, v9
	v_lshlrev_b32_e32 v12, 1, v9
	v_and_or_b32 v10, v9, s4, v10
	v_and_b32_e32 v11, 4, v11
	v_and_b32_e32 v12, 24, v12
	v_or3_b32 v10, v10, v11, v12
	v_mul_i32_i24_e32 v12, 64, v5
	v_sub_u32_e32 v7, v7, v12
	s_lshl_b32 s7, s2, 10
	v_lshlrev_b32_e32 v11, 5, v6
	v_ashrrev_i16_sdwa v7, v180, sext(v7) dst_sel:DWORD dst_unused:UNUSED_PAD src0_sel:DWORD src1_sel:BYTE_0
	v_readlane_b32 s10, v243, 40
	v_and_b32_e32 v11, 32, v11
	v_bfe_i32 v7, v7, 0, 16
	v_readlane_b32 s11, v243, 41
	s_add_u32 s34, s5, s10
	v_add_lshl_u32 v11, v11, v7, 1
	s_addc_u32 s35, s6, s11
	s_add_i32 s14, s7, 32
	v_lshl_add_u32 v154, v10, 11, v11
	s_add_i32 m0, s14, 0x10000
	v_readlane_b32 s10, v243, 44
	global_load_lds_dwordx4 v154, s[34:35]
	s_add_i32 m0, s14, 0x12000
	v_lshl_add_u32 v134, v9, 11, v11
	global_load_lds_dwordx4 v130, s[34:35]
	s_mov_b32 m0, s14
	v_readlane_b32 s11, v243, 45
	s_add_i32 s20, s14, 0x2000
	s_nop 3
	global_load_lds_dwordx4 v134, s[10:11]
	s_mov_b32 m0, s20
	s_nop 0
	global_load_lds_dwordx4 v132, s[10:11]
	s_add_u32 s10, s34, 0x40000
	s_addc_u32 s11, s35, 0
	s_add_i32 m0, s14, 0x14000
	s_add_i32 s21, s14, 0x4000
	global_load_lds_dwordx4 v154, s[10:11]
	s_add_i32 m0, s14, 0x16000
	s_add_i32 s22, s14, 0x6000
	global_load_lds_dwordx4 v130, s[10:11]
	v_readlane_b32 s10, v243, 46
	s_mov_b32 m0, s21
	v_readlane_b32 s11, v243, 47
	s_cmp_lg_u32 s3, 1
	s_nop 3
	global_load_lds_dwordx4 v134, s[10:11]
	s_mov_b32 m0, s22
	s_nop 0
	global_load_lds_dwordx4 v132, s[10:11]
	s_cbranch_scc1 .LBB0_926
	s_barrier
	s_setprio 1

.LBB0_935:
	s_add_u32 s2, s12, 0xfffc0080
	s_addc_u32 s3, s13, -1
	s_add_i32 s38, 32, 0x10000
	v_add_u32_e32 v152, s38, v145
	ds_read_b128 v[140:143], v152
	ds_read_b128 v[148:151], v152 offset:1024
	ds_read_b128 v[164:167], v152 offset:2048
	ds_read_b128 v[168:171], v152 offset:3072
	s_cmp_eq_u32 vcc_hi, 12
	s_cselect_b32 s3, s31, s3
	s_cselect_b32 s2, s4, s2
	s_cselect_b32 s19, s11, s35
	s_cselect_b32 s18, vcc_lo, s34
	v_lshl_add_u64 v[152:153], s[12:13], 0, v[136:137]
	s_add_i32 m0, s14, 0xc000
	ds_read_b128 v[172:175], v147
	ds_read_b128 v[176:179], v147 offset:1024
	ds_read_b128 v[182:185], v147 offset:2048
	ds_read_b128 v[186:189], v147 offset:3072
	ds_read_b128 v[190:193], v147 offset:4096
	ds_read_b128 v[194:197], v147 offset:5120
	ds_read_b128 v[198:201], v147 offset:6144
	ds_read_b128 v[202:205], v147 offset:7168
	global_load_lds_dwordx4 v[152:153], off
	v_lshl_add_u64 v[152:153], s[12:13], 0, v[138:139]
	s_add_i32 m0, s14, 0xe000
	s_nop 0
	global_load_lds_dwordx4 v[152:153], off
	s_waitcnt lgkmcnt(8)
	s_barrier
	s_waitcnt lgkmcnt(0)
	s_waitcnt lgkmcnt(0)
	v_mfma_f32_16x16x32_bf16 v[126:129], v[140:143], v[172:175], v[126:129]
	v_mfma_f32_16x16x32_bf16 v[122:125], v[164:167], v[172:175], v[122:125]
	v_mfma_f32_16x16x32_bf16 v[110:113], v[140:143], v[182:185], v[110:113]
	v_mfma_f32_16x16x32_bf16 v[106:109], v[164:167], v[182:185], v[106:109]
	v_mfma_f32_16x16x32_bf16 v[94:97], v[140:143], v[190:193], v[94:97]
	v_mfma_f32_16x16x32_bf16 v[90:93], v[164:167], v[190:193], v[90:93]
	v_mfma_f32_16x16x32_bf16 v[78:81], v[140:143], v[198:201], v[78:81]
	v_mfma_f32_16x16x32_bf16 v[74:77], v[164:167], v[198:201], v[74:77]
	v_mfma_f32_16x16x32_bf16 v[126:129], v[148:151], v[176:179], v[126:129]
	v_mfma_f32_16x16x32_bf16 v[122:125], v[168:171], v[176:179], v[122:125]
	v_mfma_f32_16x16x32_bf16 v[110:113], v[148:151], v[186:189], v[110:113]
	v_mfma_f32_16x16x32_bf16 v[106:109], v[168:171], v[186:189], v[106:109]
	v_mfma_f32_16x16x32_bf16 v[94:97], v[148:151], v[194:197], v[94:97]
	v_mfma_f32_16x16x32_bf16 v[90:93], v[168:171], v[194:197], v[90:93]
	v_mfma_f32_16x16x32_bf16 v[78:81], v[148:151], v[202:205], v[78:81]
	v_mfma_f32_16x16x32_bf16 v[74:77], v[168:171], v[202:205], v[74:77]
	s_barrier
	s_add_i32 s24, 32, 0x14000
	v_add_u32_e32 v152, s24, v145
	s_add_i32 s38, s38, s7
	ds_read_b128 v[206:209], v152
	ds_read_b128 v[210:213], v152 offset:1024
	ds_read_b128 v[214:217], v152 offset:2048
	ds_read_b128 v[218:221], v152 offset:3072
	v_lshl_add_u64 v[152:153], s[18:19], 0, v[154:155]
	s_mov_b32 m0, s38
	v_lshl_add_u64 v[222:223], s[18:19], 0, v[130:131]
	global_load_lds_dwordx4 v[152:153], off
	s_add_i32 m0, s38, 0x2000
	s_nop 0
	global_load_lds_dwordx4 v[222:223], off
	s_barrier
	s_waitcnt lgkmcnt(0)
	s_waitcnt lgkmcnt(0)
	v_mfma_f32_16x16x32_bf16 v[118:121], v[206:209], v[172:175], v[118:121]
	v_mfma_f32_16x16x32_bf16 v[114:117], v[214:217], v[172:175], v[114:117]
	v_mfma_f32_16x16x32_bf16 v[102:105], v[206:209], v[182:185], v[102:105]
	v_mfma_f32_16x16x32_bf16 v[98:101], v[214:217], v[182:185], v[98:101]
	v_mfma_f32_16x16x32_bf16 v[86:89], v[206:209], v[190:193], v[86:89]
	v_mfma_f32_16x16x32_bf16 v[82:85], v[214:217], v[190:193], v[82:85]
	v_mfma_f32_16x16x32_bf16 v[70:73], v[206:209], v[198:201], v[70:73]
	v_mfma_f32_16x16x32_bf16 v[66:69], v[214:217], v[198:201], v[66:69]
	v_mfma_f32_16x16x32_bf16 v[118:121], v[210:213], v[176:179], v[118:121]
	v_mfma_f32_16x16x32_bf16 v[114:117], v[218:221], v[176:179], v[114:117]
	v_mfma_f32_16x16x32_bf16 v[102:105], v[210:213], v[186:189], v[102:105]
	v_mfma_f32_16x16x32_bf16 v[98:101], v[218:221], v[186:189], v[98:101]
	v_mfma_f32_16x16x32_bf16 v[86:89], v[210:213], v[194:197], v[86:89]
	v_mfma_f32_16x16x32_bf16 v[82:85], v[218:221], v[194:197], v[82:85]
	v_mfma_f32_16x16x32_bf16 v[70:73], v[210:213], v[202:205], v[70:73]
	v_mfma_f32_16x16x32_bf16 v[66:69], v[218:221], v[202:205], v[66:69]
	s_mov_b32 m0, s14
	v_lshl_add_u64 v[224:225], s[2:3], 0, v[134:135]
	s_barrier
	ds_read_b128 v[172:175], v147 offset:16384
	ds_read_b128 v[176:179], v147 offset:17408
	ds_read_b128 v[182:185], v147 offset:18432
	ds_read_b128 v[186:189], v147 offset:19456
	ds_read_b128 v[190:193], v147 offset:20480
	ds_read_b128 v[194:197], v147 offset:21504
	ds_read_b128 v[198:201], v147 offset:22528
	ds_read_b128 v[202:205], v147 offset:23552
	global_load_lds_dwordx4 v[224:225], off
	v_lshl_add_u64 v[226:227], s[2:3], 0, v[132:133]
	s_mov_b32 m0, s20
	s_nop 0
	global_load_lds_dwordx4 v[226:227], off
	s_barrier
	s_waitcnt lgkmcnt(0)
	s_waitcnt lgkmcnt(0)
	v_mfma_f32_16x16x32_bf16 v[62:65], v[140:143], v[172:175], v[62:65]
	v_mfma_f32_16x16x32_bf16 v[58:61], v[164:167], v[172:175], v[58:61]
	v_mfma_f32_16x16x32_bf16 v[46:49], v[140:143], v[182:185], v[46:49]
	v_mfma_f32_16x16x32_bf16 v[42:45], v[164:167], v[182:185], v[42:45]
	v_mfma_f32_16x16x32_bf16 v[30:33], v[140:143], v[190:193], v[30:33]
	v_mfma_f32_16x16x32_bf16 v[26:29], v[164:167], v[190:193], v[26:29]
	v_mfma_f32_16x16x32_bf16 v[14:17], v[140:143], v[198:201], v[14:17]
	v_mfma_f32_16x16x32_bf16 v[10:13], v[164:167], v[198:201], v[10:13]
	v_mfma_f32_16x16x32_bf16 v[62:65], v[148:151], v[176:179], v[62:65]
	v_mfma_f32_16x16x32_bf16 v[58:61], v[168:171], v[176:179], v[58:61]
	v_mfma_f32_16x16x32_bf16 v[46:49], v[148:151], v[186:189], v[46:49]
	v_mfma_f32_16x16x32_bf16 v[42:45], v[168:171], v[186:189], v[42:45]
	v_mfma_f32_16x16x32_bf16 v[30:33], v[148:151], v[194:197], v[30:33]
	v_mfma_f32_16x16x32_bf16 v[26:29], v[168:171], v[194:197], v[26:29]
	v_mfma_f32_16x16x32_bf16 v[14:17], v[148:151], v[202:205], v[14:17]
	v_mfma_f32_16x16x32_bf16 v[10:13], v[168:171], v[202:205], v[10:13]
	s_barrier
	s_add_u32 s38, s18, 0x40000
	s_addc_u32 s39, s19, 0
	s_add_i32 s24, s24, s7
	v_lshl_add_u64 v[140:141], s[38:39], 0, v[154:155]
	s_mov_b32 m0, s24
	s_nop 0
	global_load_lds_dwordx4 v[140:141], off
	v_lshl_add_u64 v[140:141], s[38:39], 0, v[130:131]
	s_add_i32 m0, s24, 0x2000
	s_nop 0
	global_load_lds_dwordx4 v[140:141], off
	s_waitcnt vmcnt(6)
	s_barrier
	v_mfma_f32_16x16x32_bf16 v[54:57], v[206:209], v[172:175], v[54:57]
	v_mfma_f32_16x16x32_bf16 v[50:53], v[214:217], v[172:175], v[50:53]
	v_mfma_f32_16x16x32_bf16 v[38:41], v[206:209], v[182:185], v[38:41]
	v_mfma_f32_16x16x32_bf16 v[34:37], v[214:217], v[182:185], v[34:37]
	v_mfma_f32_16x16x32_bf16 v[22:25], v[206:209], v[190:193], v[22:25]
	v_mfma_f32_16x16x32_bf16 v[18:21], v[214:217], v[190:193], v[18:21]
	v_mfma_f32_16x16x32_bf16 v[6:9], v[206:209], v[198:201], v[6:9]
	v_mfma_f32_16x16x32_bf16 v[2:5], v[214:217], v[198:201], v[2:5]
	v_mfma_f32_16x16x32_bf16 v[54:57], v[210:213], v[176:179], v[54:57]
	v_mfma_f32_16x16x32_bf16 v[50:53], v[218:221], v[176:179], v[50:53]
	v_mfma_f32_16x16x32_bf16 v[38:41], v[210:213], v[186:189], v[38:41]
	v_mfma_f32_16x16x32_bf16 v[34:37], v[218:221], v[186:189], v[34:37]
	v_mfma_f32_16x16x32_bf16 v[22:25], v[210:213], v[194:197], v[22:25]
	v_mfma_f32_16x16x32_bf16 v[18:21], v[218:221], v[194:197], v[18:21]
	v_mfma_f32_16x16x32_bf16 v[6:9], v[210:213], v[202:205], v[6:9]
	v_mfma_f32_16x16x32_bf16 v[2:5], v[218:221], v[202:205], v[2:5]
	s_add_i32 s24, 32, 0x18000
	v_add_u32_e32 v168, s24, v145
	s_barrier
	ds_read_b128 v[140:143], v168
	ds_read_b128 v[148:151], v168 offset:1024
	ds_read_b128 v[164:167], v168 offset:2048
	ds_read_b128 v[168:171], v168 offset:3072
	s_add_u32 s2, s2, 0x40000
	s_addc_u32 s3, s3, 0
	s_mov_b32 m0, s21
	v_lshl_add_u64 v[206:207], s[2:3], 0, v[134:135]
	ds_read_b128 v[172:175], v147 offset:32768
	ds_read_b128 v[176:179], v147 offset:33792
	ds_read_b128 v[182:185], v147 offset:34816
	ds_read_b128 v[186:189], v147 offset:35840
	ds_read_b128 v[190:193], v147 offset:36864
	ds_read_b128 v[194:197], v147 offset:37888
	ds_read_b128 v[198:201], v147 offset:38912
	ds_read_b128 v[202:205], v147 offset:39936
	global_load_lds_dwordx4 v[206:207], off
	v_lshl_add_u64 v[206:207], s[2:3], 0, v[132:133]
	s_mov_b32 m0, s22
	s_nop 0
	global_load_lds_dwordx4 v[206:207], off
	s_waitcnt lgkmcnt(8)
	s_barrier
	s_waitcnt lgkmcnt(0)
	s_waitcnt lgkmcnt(0)
	v_mfma_f32_16x16x32_bf16 v[126:129], v[140:143], v[172:175], v[126:129]
	v_mfma_f32_16x16x32_bf16 v[122:125], v[164:167], v[172:175], v[122:125]
	v_mfma_f32_16x16x32_bf16 v[110:113], v[140:143], v[182:185], v[110:113]
	v_mfma_f32_16x16x32_bf16 v[106:109], v[164:167], v[182:185], v[106:109]
	v_mfma_f32_16x16x32_bf16 v[94:97], v[140:143], v[190:193], v[94:97]
	v_mfma_f32_16x16x32_bf16 v[90:93], v[164:167], v[190:193], v[90:93]
	v_mfma_f32_16x16x32_bf16 v[78:81], v[140:143], v[198:201], v[78:81]
	v_mfma_f32_16x16x32_bf16 v[74:77], v[164:167], v[198:201], v[74:77]
	v_mfma_f32_16x16x32_bf16 v[126:129], v[148:151], v[176:179], v[126:129]
	v_mfma_f32_16x16x32_bf16 v[122:125], v[168:171], v[176:179], v[122:125]
	v_mfma_f32_16x16x32_bf16 v[110:113], v[148:151], v[186:189], v[110:113]
	v_mfma_f32_16x16x32_bf16 v[106:109], v[168:171], v[186:189], v[106:109]
	v_mfma_f32_16x16x32_bf16 v[94:97], v[148:151], v[194:197], v[94:97]
	v_mfma_f32_16x16x32_bf16 v[90:93], v[168:171], v[194:197], v[90:93]
	v_mfma_f32_16x16x32_bf16 v[78:81], v[148:151], v[202:205], v[78:81]
	v_mfma_f32_16x16x32_bf16 v[74:77], v[168:171], v[202:205], v[74:77]
	s_barrier
	s_add_i32 s38, 32, 0x1c000
	s_add_i32 s2, s24, s7
	v_add_u32_e32 v218, s38, v145
	v_lshl_add_u64 v[152:153], v[152:153], 0, s[44:45]
	s_mov_b32 m0, s2
	ds_read_b128 v[206:209], v218
	ds_read_b128 v[210:213], v218 offset:1024
	ds_read_b128 v[214:217], v218 offset:2048
	ds_read_b128 v[218:221], v218 offset:3072
	global_load_lds_dwordx4 v[152:153], off
	v_lshl_add_u64 v[152:153], v[222:223], 0, s[44:45]
	s_add_i32 m0, s2, 0x2000
	s_nop 0
	global_load_lds_dwordx4 v[152:153], off
	s_barrier
	s_waitcnt lgkmcnt(0)
	s_waitcnt lgkmcnt(0)
	v_mfma_f32_16x16x32_bf16 v[118:121], v[206:209], v[172:175], v[118:121]
	v_mfma_f32_16x16x32_bf16 v[114:117], v[214:217], v[172:175], v[114:117]
	v_mfma_f32_16x16x32_bf16 v[102:105], v[206:209], v[182:185], v[102:105]
	v_mfma_f32_16x16x32_bf16 v[98:101], v[214:217], v[182:185], v[98:101]
	v_mfma_f32_16x16x32_bf16 v[86:89], v[206:209], v[190:193], v[86:89]
	v_mfma_f32_16x16x32_bf16 v[82:85], v[214:217], v[190:193], v[82:85]
	v_mfma_f32_16x16x32_bf16 v[70:73], v[206:209], v[198:201], v[70:73]
	v_mfma_f32_16x16x32_bf16 v[66:69], v[214:217], v[198:201], v[66:69]
	v_mfma_f32_16x16x32_bf16 v[118:121], v[210:213], v[176:179], v[118:121]
	v_mfma_f32_16x16x32_bf16 v[114:117], v[218:221], v[176:179], v[114:117]
	v_mfma_f32_16x16x32_bf16 v[102:105], v[210:213], v[186:189], v[102:105]
	v_mfma_f32_16x16x32_bf16 v[98:101], v[218:221], v[186:189], v[98:101]
	v_mfma_f32_16x16x32_bf16 v[86:89], v[210:213], v[194:197], v[86:89]
	v_mfma_f32_16x16x32_bf16 v[82:85], v[218:221], v[194:197], v[82:85]
	v_mfma_f32_16x16x32_bf16 v[70:73], v[210:213], v[202:205], v[70:73]
	v_mfma_f32_16x16x32_bf16 v[66:69], v[218:221], v[202:205], v[66:69]
	s_mov_b32 m0, s23
	v_lshl_add_u64 v[152:153], v[224:225], 0, s[44:45]
	s_barrier
	ds_read_b128 v[172:175], v147 offset:49152
	ds_read_b128 v[176:179], v147 offset:50176
	ds_read_b128 v[182:185], v147 offset:51200
	ds_read_b128 v[186:189], v147 offset:52224
	ds_read_b128 v[190:193], v147 offset:53248
	ds_read_b128 v[194:197], v147 offset:54272
	ds_read_b128 v[198:201], v147 offset:55296
	ds_read_b128 v[202:205], v147 offset:56320
	global_load_lds_dwordx4 v[152:153], off
	v_lshl_add_u64 v[152:153], v[226:227], 0, s[44:45]
	s_mov_b32 m0, s28
	s_nop 0
	global_load_lds_dwordx4 v[152:153], off
	s_barrier
	s_waitcnt lgkmcnt(0)
	s_waitcnt lgkmcnt(0)
	v_mfma_f32_16x16x32_bf16 v[62:65], v[140:143], v[172:175], v[62:65]
	v_mfma_f32_16x16x32_bf16 v[58:61], v[164:167], v[172:175], v[58:61]
	v_mfma_f32_16x16x32_bf16 v[46:49], v[140:143], v[182:185], v[46:49]
	v_mfma_f32_16x16x32_bf16 v[42:45], v[164:167], v[182:185], v[42:45]
	v_mfma_f32_16x16x32_bf16 v[30:33], v[140:143], v[190:193], v[30:33]
	v_mfma_f32_16x16x32_bf16 v[26:29], v[164:167], v[190:193], v[26:29]
	v_mfma_f32_16x16x32_bf16 v[14:17], v[140:143], v[198:201], v[14:17]
	v_mfma_f32_16x16x32_bf16 v[10:13], v[164:167], v[198:201], v[10:13]
	v_mfma_f32_16x16x32_bf16 v[62:65], v[148:151], v[176:179], v[62:65]
	v_mfma_f32_16x16x32_bf16 v[58:61], v[168:171], v[176:179], v[58:61]
	v_mfma_f32_16x16x32_bf16 v[46:49], v[148:151], v[186:189], v[46:49]
	v_mfma_f32_16x16x32_bf16 v[42:45], v[168:171], v[186:189], v[42:45]
	v_mfma_f32_16x16x32_bf16 v[30:33], v[148:151], v[194:197], v[30:33]
	v_mfma_f32_16x16x32_bf16 v[26:29], v[168:171], v[194:197], v[26:29]
	v_mfma_f32_16x16x32_bf16 v[14:17], v[148:151], v[202:205], v[14:17]
	v_mfma_f32_16x16x32_bf16 v[10:13], v[168:171], v[202:205], v[10:13]
	s_barrier
	s_add_u32 s2, s18, 0x40080
	s_addc_u32 s3, s19, 0
	s_add_i32 s18, s38, s7
	v_lshl_add_u64 v[140:141], s[2:3], 0, v[154:155]
	s_mov_b32 m0, s18
	s_nop 0
	global_load_lds_dwordx4 v[140:141], off
	v_lshl_add_u64 v[140:141], s[2:3], 0, v[130:131]
	s_add_i32 m0, s18, 0x2000
	s_nop 0
	global_load_lds_dwordx4 v[140:141], off
	s_waitcnt vmcnt(6)
	s_barrier
	v_mfma_f32_16x16x32_bf16 v[54:57], v[206:209], v[172:175], v[54:57]
	v_mfma_f32_16x16x32_bf16 v[50:53], v[214:217], v[172:175], v[50:53]
	v_mfma_f32_16x16x32_bf16 v[38:41], v[206:209], v[182:185], v[38:41]
	v_mfma_f32_16x16x32_bf16 v[34:37], v[214:217], v[182:185], v[34:37]
	v_mfma_f32_16x16x32_bf16 v[22:25], v[206:209], v[190:193], v[22:25]
	v_mfma_f32_16x16x32_bf16 v[18:21], v[214:217], v[190:193], v[18:21]
	v_mfma_f32_16x16x32_bf16 v[6:9], v[206:209], v[198:201], v[6:9]
	v_mfma_f32_16x16x32_bf16 v[2:5], v[214:217], v[198:201], v[2:5]
	v_mfma_f32_16x16x32_bf16 v[54:57], v[210:213], v[176:179], v[54:57]
	v_mfma_f32_16x16x32_bf16 v[50:53], v[218:221], v[176:179], v[50:53]
	v_mfma_f32_16x16x32_bf16 v[38:41], v[210:213], v[186:189], v[38:41]
	v_mfma_f32_16x16x32_bf16 v[34:37], v[218:221], v[186:189], v[34:37]
	v_mfma_f32_16x16x32_bf16 v[22:25], v[210:213], v[194:197], v[22:25]
	v_mfma_f32_16x16x32_bf16 v[18:21], v[218:221], v[194:197], v[18:21]
	v_mfma_f32_16x16x32_bf16 v[6:9], v[210:213], v[202:205], v[6:9]
	v_mfma_f32_16x16x32_bf16 v[2:5], v[218:221], v[202:205], v[2:5]
	s_add_i32 vcc_hi, vcc_hi, 2
	s_add_u32 s12, s12, 0x100
	s_addc_u32 s13, s13, 0
	s_add_u32 s34, s34, 0x100
	s_addc_u32 s35, s35, 0
	s_cmp_gt_u32 vcc_hi, 13
	s_barrier
	s_cbranch_scc0 .LBB0_935
	v_lshl_add_u32 v142, s36, 8, v144
	v_ashrrev_i32_e32 v143, 31, v142
	v_lshl_or_b32 v140, s37, 8, v146
	v_lshlrev_b64 v[150:151], 11, v[142:143]
	v_ashrrev_i32_e32 v141, 31, v140
	v_lshl_add_u64 v[150:151], s[58:59], 0, v[150:151]
	v_lshl_add_u64 v[164:165], v[140:141], 1, v[150:151]
	v_mov_b64_e32 v[238:239], v[164:165]
	global_load_dwordx4 v[150:153], v[164:165], off
	s_nop 0
	global_load_dwordx4 v[164:167], v[164:165], off offset:256
	v_add_co_u32_e32 v240, vcc, 0x8000, v238
	s_nop 1
	v_addc_co_u32_e32 v241, vcc, 0, v239, vcc
	global_load_dwordx4 v[182:185], v[240:241], off
	global_load_dwordx4 v[186:189], v[240:241], off offset:256
	v_add_co_u32_e32 v240, vcc, 0x10000, v238
	s_nop 1
	v_addc_co_u32_e32 v241, vcc, 0, v239, vcc
	global_load_dwordx4 v[190:193], v[240:241], off
	global_load_dwordx4 v[194:197], v[240:241], off offset:256
	v_add_co_u32_e32 v240, vcc, 0x18000, v238
	s_nop 1
	v_addc_co_u32_e32 v241, vcc, 0, v239, vcc
	global_load_dwordx4 v[198:201], v[240:241], off
	global_load_dwordx4 v[202:205], v[240:241], off offset:256
	v_add_co_u32_e32 v240, vcc, 0x40000, v238
	s_nop 1
	v_addc_co_u32_e32 v241, vcc, 0, v239, vcc
	global_load_dwordx4 v[206:209], v[240:241], off
	global_load_dwordx4 v[210:213], v[240:241], off offset:256
	v_add_co_u32_e32 v240, vcc, 0x48000, v238
	s_nop 1
	v_addc_co_u32_e32 v241, vcc, 0, v239, vcc
	global_load_dwordx4 v[214:217], v[240:241], off
	global_load_dwordx4 v[218:221], v[240:241], off offset:256
	v_add_co_u32_e32 v240, vcc, 0x50000, v238
	s_nop 1
	v_addc_co_u32_e32 v241, vcc, 0, v239, vcc
	global_load_dwordx4 v[222:225], v[240:241], off
	global_load_dwordx4 v[226:229], v[240:241], off offset:256
	v_add_co_u32_e32 v240, vcc, 0x58000, v238
	s_nop 1
	v_addc_co_u32_e32 v241, vcc, 0, v239, vcc
	global_load_dwordx4 v[230:233], v[240:241], off
	global_load_dwordx4 v[234:237], v[240:241], off offset:256
	v_lshlrev_b32_e32 v148, 1, v140
	s_waitcnt vmcnt(14)
	v_lshlrev_b32_e32 v149, 16, v150
	v_lshlrev_b32_e32 v171, 16, v164
	v_and_b32_e32 v164, 0xffff0000, v164
	v_and_b32_e32 v150, 0xffff0000, v150
	v_lshlrev_b32_e32 v168, 16, v151
	v_and_b32_e32 v151, 0xffff0000, v151
	v_lshlrev_b32_e32 v173, 16, v166
	v_and_b32_e32 v166, 0xffff0000, v166
	v_lshlrev_b32_e32 v174, 16, v167
	v_and_b32_e32 v167, 0xffff0000, v167
	v_add_f32_e32 v118, v118, v171
	v_add_f32_e32 v119, v119, v164
	v_lshlrev_b32_e32 v172, 16, v165
	v_add_f32_e32 v126, v126, v149
	v_add_f32_e32 v149, v114, v173
	v_add_f32_e32 v114, v127, v150
	v_add_f32_e32 v127, v115, v166
	v_add_f32_e32 v115, v128, v168
	v_add_f32_e32 v128, v116, v174
	v_add_f32_e32 v116, v129, v151
	v_add_f32_e32 v129, v117, v167
	v_mul_f32_e32 v117, v118, v118
	v_mul_f32_e32 v150, v119, v119
	v_add_f32_e32 v120, v120, v172
	v_fmac_f32_e32 v117, v126, v126
	v_fmac_f32_e32 v150, v114, v114
	v_and_b32_e32 v165, 0xffff0000, v165
	v_add_f32_e32 v117, v117, v150
	v_mul_f32_e32 v150, v120, v120
	v_add_f32_e32 v121, v121, v165
	v_fmac_f32_e32 v150, v115, v115
	v_add_f32_e32 v117, v150, v117
	v_mul_f32_e32 v150, v121, v121
	v_lshlrev_b32_e32 v169, 16, v152
	v_fmac_f32_e32 v150, v116, v116
	v_add_f32_e32 v122, v122, v169
	v_add_f32_e32 v117, v150, v117
	v_mul_f32_e32 v150, v149, v149
	v_and_b32_e32 v152, 0xffff0000, v152
	v_fmac_f32_e32 v150, v122, v122
	v_add_f32_e32 v123, v123, v152
	v_add_f32_e32 v117, v150, v117
	v_mul_f32_e32 v150, v127, v127
	v_lshlrev_b32_e32 v170, 16, v153
	v_fmac_f32_e32 v150, v123, v123
	v_add_f32_e32 v124, v124, v170
	v_add_f32_e32 v117, v150, v117
	v_mul_f32_e32 v150, v128, v128
	v_and_b32_e32 v153, 0xffff0000, v153
	v_fmac_f32_e32 v150, v124, v124
	v_add_f32_e32 v125, v125, v153
	v_add_f32_e32 v117, v150, v117
	v_mul_f32_e32 v150, v129, v129
	v_fmac_f32_e32 v150, v125, v125
	v_lshl_add_u32 v151, v142, 11, v148
	v_cvt_pk_bf16_f32 v114, v126, v114
	v_cvt_pk_bf16_f32 v115, v115, v116
	v_add_f32_e32 v150, v150, v117
	v_cvt_pk_bf16_f32 v116, v122, v123
	v_cvt_pk_bf16_f32 v117, v124, v125
	buffer_store_dwordx4 v[114:117], v151, s[64:67], 0 offen sc1
	s_nop 1
	v_cvt_pk_bf16_f32 v114, v118, v119
	v_cvt_pk_bf16_f32 v115, v120, v121
	v_cvt_pk_bf16_f32 v116, v149, v127
	v_cvt_pk_bf16_f32 v117, v128, v129
	buffer_store_dwordx4 v[114:117], v151, s[64:67], 0 offen offset:256 sc1
	s_nop 1
	v_and_b32_e32 v115, 64, v181
	v_xor_b32_e32 v114, 16, v181
	v_add_u32_e32 v115, 64, v115
	v_cmp_lt_i32_e32 vcc, v114, v115
	v_xor_b32_e32 v117, 32, v181
	s_nop 0
	v_cndmask_b32_e32 v114, v181, v114, vcc
	v_lshlrev_b32_e32 v116, 2, v114
	ds_bpermute_b32 v114, v116, v150
	v_cmp_lt_i32_e32 vcc, v117, v115
	s_waitcnt lgkmcnt(0)
	v_add_f32_e32 v114, v150, v114
	v_cndmask_b32_e32 v115, v181, v117, vcc
	v_lshlrev_b32_e32 v117, 2, v115
	ds_bpermute_b32 v115, v117, v114
	s_and_saveexec_b64 s[2:3], s[40:41]
	s_cbranch_execz .LBB0_938
	v_lshl_add_u64 v[118:119], v[142:143], 2, s[0:1]
	s_waitcnt lgkmcnt(0)
	v_add_f32_e32 v114, v114, v115
	global_atomic_add_f32 v[118:119], v114, off

.LBB0_952:
	s_setprio 0
	s_waitcnt vmcnt(0)
	v_readlane_b32 s2, v242, 55
	v_readlane_b32 s12, v242, 51
	v_readlane_b32 s16, v242, 53
	s_cmpk_gt_u32 s2, 0xff
	v_readlane_b32 s20, v242, 43
	v_readlane_b32 s21, v242, 44
	v_readlane_b32 s28, v242, 45
	v_readlane_b32 s29, v242, 46
	v_readlane_b32 s13, v242, 52
	v_readlane_b32 s17, v242, 54
	s_cbranch_scc1 .LBB0_954
	s_barrier

.LBB0_959:
	s_and_b32 s3, s5, 0x3c0
	v_or_b32_e32 v2, s3, v43
	v_lshlrev_b32_e32 v154, 11, v2
	s_and_b32 s2, s4, 0xffffffe0
	v_lshl_add_u64 v[60:61], v[38:39], 0, v[154:155]
	v_add_u32_e32 v40, s2, v42
	v_ashrrev_i32_e32 v41, 31, v40
	v_lshlrev_b64 v[62:63], 11, v[40:41]
	v_lshl_add_u64 v[64:65], v[36:37], 0, v[62:63]
	s_mov_b32 s2, 0x10000
	v_add_co_u32_e32 v66, vcc, s2, v60
	s_mov_b32 s2, 0x7060302
	s_nop 0
	v_addc_co_u32_e32 v67, vcc, 0, v61, vcc
	global_load_dwordx4 v[68:71], v[60:61], off
	global_load_dwordx4 v[100:103], v[64:65], off
	global_load_dwordx4 v[182:185], v[66:67], off
	global_load_dwordx4 v[72:75], v[60:61], off offset:32
	global_load_dwordx4 v[104:107], v[64:65], off offset:32
	global_load_dwordx4 v[186:189], v[66:67], off offset:32
	global_load_dwordx4 v[76:79], v[60:61], off offset:64
	global_load_dwordx4 v[108:111], v[64:65], off offset:64
	global_load_dwordx4 v[190:193], v[66:67], off offset:64
	global_load_dwordx4 v[80:83], v[60:61], off offset:96
	global_load_dwordx4 v[112:115], v[64:65], off offset:96
	global_load_dwordx4 v[194:197], v[66:67], off offset:96
	global_load_dwordx4 v[84:87], v[60:61], off offset:128
	global_load_dwordx4 v[116:119], v[64:65], off offset:128
	global_load_dwordx4 v[198:201], v[66:67], off offset:128
	global_load_dwordx4 v[88:91], v[60:61], off offset:160
	global_load_dwordx4 v[120:123], v[64:65], off offset:160
	global_load_dwordx4 v[202:205], v[66:67], off offset:160
	global_load_dwordx4 v[92:95], v[60:61], off offset:192
	global_load_dwordx4 v[124:127], v[64:65], off offset:192
	global_load_dwordx4 v[206:209], v[66:67], off offset:192
	global_load_dwordx4 v[96:99], v[60:61], off offset:224
	global_load_dwordx4 v[128:131], v[64:65], off offset:224
	global_load_dwordx4 v[210:213], v[66:67], off offset:224
	v_lshl_add_u64 v[60:61], s[58:59], 0, v[62:63]
	v_add_u32_e32 v56, s3, v44
	v_or_b32_e32 v58, v56, v34
	v_ashrrev_i32_e32 v59, 31, v58
	v_lshl_add_u64 v[58:59], v[58:59], 1, v[60:61]
	v_ashrrev_i32_e32 v57, 31, v56
	v_lshl_add_u64 v[216:217], v[56:57], 0, v[34:35]
	v_lshl_add_u64 v[216:217], v[216:217], 1, v[60:61]
	global_load_dword v214, v[58:59], off
	global_load_dword v215, v[216:217], off offset:64
	s_waitcnt vmcnt(23)
	v_mfma_f32_32x32x16_bf16 v[2:17], v[68:71], v[100:103], 0
	v_mfma_f32_32x32x16_bf16 v[18:33], v[182:185], v[100:103], 0
	s_waitcnt vmcnt(20)
	v_mfma_f32_32x32x16_bf16 v[2:17], v[72:75], v[104:107], v[2:17]
	v_mfma_f32_32x32x16_bf16 v[18:33], v[186:189], v[104:107], v[18:33]
	s_waitcnt vmcnt(17)
	v_mfma_f32_32x32x16_bf16 v[2:17], v[76:79], v[108:111], v[2:17]
	v_mfma_f32_32x32x16_bf16 v[18:33], v[190:193], v[108:111], v[18:33]
	s_waitcnt vmcnt(14)
	v_mfma_f32_32x32x16_bf16 v[2:17], v[80:83], v[112:115], v[2:17]
	v_mfma_f32_32x32x16_bf16 v[18:33], v[194:197], v[112:115], v[18:33]
	s_waitcnt vmcnt(11)
	v_mfma_f32_32x32x16_bf16 v[2:17], v[84:87], v[116:119], v[2:17]
	v_mfma_f32_32x32x16_bf16 v[18:33], v[198:201], v[116:119], v[18:33]
	s_waitcnt vmcnt(8)
	v_mfma_f32_32x32x16_bf16 v[2:17], v[88:91], v[120:123], v[2:17]
	v_mfma_f32_32x32x16_bf16 v[18:33], v[202:205], v[120:123], v[18:33]
	s_waitcnt vmcnt(5)
	v_mfma_f32_32x32x16_bf16 v[2:17], v[92:95], v[124:127], v[2:17]
	v_mfma_f32_32x32x16_bf16 v[18:33], v[206:209], v[124:127], v[18:33]
	s_waitcnt vmcnt(2)
	v_mfma_f32_32x32x16_bf16 v[2:17], v[96:99], v[128:131], v[2:17]
	v_mfma_f32_32x32x16_bf16 v[18:33], v[210:213], v[128:131], v[18:33]
	s_nop 7
	s_nop 4
	ds_write2st64_b32 v46, v2, v3 offset1:1
	ds_write2st64_b32 v46, v4, v5 offset0:2 offset1:3
	ds_write2st64_b32 v46, v6, v7 offset0:4 offset1:5
	ds_write2st64_b32 v46, v8, v9 offset0:6 offset1:7
	ds_write2st64_b32 v46, v10, v11 offset0:8 offset1:9
	ds_write2st64_b32 v46, v12, v13 offset0:10 offset1:11
	ds_write2st64_b32 v46, v14, v15 offset0:12 offset1:13
	ds_write2st64_b32 v46, v16, v17 offset0:14 offset1:15
	ds_write2st64_b32 v46, v18, v19 offset0:16 offset1:17
	ds_write2st64_b32 v46, v20, v21 offset0:18 offset1:19
	ds_write2st64_b32 v46, v22, v23 offset0:20 offset1:21
	ds_write2st64_b32 v46, v24, v25 offset0:22 offset1:23
	ds_write2st64_b32 v46, v26, v27 offset0:24 offset1:25
	ds_write2st64_b32 v46, v28, v29 offset0:26 offset1:27
	ds_write2st64_b32 v46, v30, v31 offset0:28 offset1:29
	ds_write2st64_b32 v46, v32, v33 offset0:30 offset1:31
	s_waitcnt lgkmcnt(0)
	s_barrier
	v_lshl_add_u64 v[2:3], v[56:57], 0, v[34:35]
	v_lshl_add_u64 v[4:5], v[2:3], 1, v[60:61]
	ds_read2st64_b32 v[2:3], v47 offset1:1
	ds_read2st64_b32 v[6:7], v47 offset0:32 offset1:33
	ds_read2st64_b32 v[8:9], v47 offset0:64 offset1:65
	ds_read2st64_b32 v[10:11], v47 offset0:96 offset1:97
	ds_read2st64_b32 v[12:13], v47 offset0:128 offset1:129
	ds_read2st64_b32 v[14:15], v47 offset0:160 offset1:161
	ds_read2st64_b32 v[16:17], v47 offset0:192 offset1:193
	ds_read2st64_b32 v[18:19], v47 offset0:224 offset1:225
	s_waitcnt lgkmcnt(7)
	v_pk_add_f32 v[2:3], v[2:3], 0 op_sel_hi:[1,0]
	s_waitcnt lgkmcnt(6)
	v_pk_add_f32 v[2:3], v[2:3], v[6:7]
	s_waitcnt vmcnt(0)
	v_and_b32_e32 v7, 0xffff0000, v214
	s_waitcnt lgkmcnt(5)
	v_pk_add_f32 v[2:3], v[2:3], v[8:9]
	v_lshlrev_b32_e32 v6, 16, v214
	s_waitcnt lgkmcnt(4)
	v_pk_add_f32 v[2:3], v[2:3], v[10:11]
	s_waitcnt lgkmcnt(3)
	v_pk_add_f32 v[2:3], v[2:3], v[12:13]
	s_waitcnt lgkmcnt(2)
	v_pk_add_f32 v[2:3], v[2:3], v[14:15]
	s_waitcnt lgkmcnt(1)
	v_pk_add_f32 v[2:3], v[2:3], v[16:17]
	s_waitcnt lgkmcnt(0)
	v_pk_add_f32 v[2:3], v[2:3], v[18:19]
	s_nop 0
	v_pk_add_f32 v[2:3], v[2:3], v[6:7]
	s_nop 0
	v_and_b32_sdwa v6, v3, v180 dst_sel:DWORD dst_unused:UNUSED_PAD src0_sel:WORD_1 src1_sel:DWORD
	v_and_b32_sdwa v7, v2, v180 dst_sel:DWORD dst_unused:UNUSED_PAD src0_sel:WORD_1 src1_sel:DWORD
	v_add3_u32 v7, v2, v7, s15
	v_add3_u32 v6, v3, v6, s15
	v_perm_b32 v6, v6, v7, s2
	global_store_dword v[58:59], v6, off sc1
	ds_read2st64_b32 v[6:7], v47 offset0:48 offset1:49
	ds_read2st64_b32 v[8:9], v47 offset0:16 offset1:17
	ds_read2st64_b32 v[10:11], v47 offset0:112 offset1:113
	ds_read2st64_b32 v[12:13], v47 offset0:80 offset1:81
	ds_read2st64_b32 v[14:15], v47 offset0:176 offset1:177
	ds_read2st64_b32 v[16:17], v47 offset0:144 offset1:145
	ds_read2st64_b32 v[18:19], v47 offset0:240 offset1:241
	ds_read2st64_b32 v[20:21], v47 offset0:208 offset1:209
	s_waitcnt lgkmcnt(6)
	v_pk_add_f32 v[8:9], v[8:9], 0 op_sel_hi:[1,0]
	v_pk_mul_f32 v[2:3], v[2:3], v[2:3]
	v_pk_add_f32 v[6:7], v[8:9], v[6:7]
	v_add_f32_e32 v8, v2, v3
	s_waitcnt lgkmcnt(4)
	v_pk_add_f32 v[6:7], v[6:7], v[12:13]
	v_and_b32_e32 v3, 0xffff0000, v215
	v_pk_add_f32 v[6:7], v[6:7], v[10:11]
	v_lshlrev_b32_e32 v2, 16, v215
	s_waitcnt lgkmcnt(2)
	v_pk_add_f32 v[6:7], v[6:7], v[16:17]
	s_nop 0
	v_pk_add_f32 v[6:7], v[6:7], v[14:15]
	s_waitcnt lgkmcnt(0)
	v_pk_add_f32 v[6:7], v[6:7], v[20:21]
	s_nop 0
	v_pk_add_f32 v[6:7], v[6:7], v[18:19]
	s_nop 0
	v_pk_add_f32 v[6:7], v[6:7], v[2:3]
	s_nop 0
	v_pk_mul_f32 v[2:3], v[6:7], v[6:7]
	v_and_b32_sdwa v9, v7, v180 dst_sel:DWORD dst_unused:UNUSED_PAD src0_sel:WORD_1 src1_sel:DWORD
	v_add_f32_e32 v2, v8, v2
	v_add_f32_e32 v2, v2, v3
	ds_bpermute_b32 v3, v45, v2
	v_and_b32_sdwa v8, v6, v180 dst_sel:DWORD dst_unused:UNUSED_PAD src0_sel:WORD_1 src1_sel:DWORD
	v_add3_u32 v6, v6, v8, s15
	v_add3_u32 v7, v7, v9, s15
	v_perm_b32 v6, v7, v6, s2
	global_store_dword v[4:5], v6, off offset:64 sc1
	s_and_saveexec_b64 s[2:3], s[36:37]
	s_cbranch_execz .LBB0_958
	v_lshl_add_u64 v[4:5], v[40:41], 2, s[0:1]
	s_waitcnt lgkmcnt(0)
	v_add_f32_e32 v2, v2, v3
	global_atomic_add_f32 v[4:5], v2, off
	s_branch .LBB0_958
